# scan streamed through LDS-DMA ring, hand-written attention units (S-transposed softmax, tr-read V, 1 barrier per key block), XCD-local unit order
# speedup vs baseline: 1.2460x; 1.0033x over previous
; DI int otid() { int t = threadIdx.x & 255; asm volatile("" : "+v"(t)); return t; }
; template <int NKB>
; DI void attn_unit(const Params& p, int l, int mode, int grp, int head, int r0, int dil, int i0, int sub_len, int W, h16* lds) {
;   unsigned char* ws = p.ws;
;   const h16* P = (const h16*)(ws + OFF_PS);
;   h16* Qi = lds; h16* Ki = lds + 64 * LDH; h16* Vt = lds + 128 * LDH; h16* Pi = lds + 192 * LDH;
;   const int tid = otid(), lane = tid & 63, w = tid >> 6, r = lane & 15, q = lane >> 4;
;   const int lrow = tid >> 2, seg = tid & 3;
;   int qcol, kcol, vcol;
;   if (mode == 0) { qcol = 1024 + grp * 256 + head * 64; kcol = 1792 + grp * 256 + head * 64; vcol = 2560 + grp * 256 + head * 64; }
;   else { qcol = 4352 + head * 64; kcol = 4864 + (head >> 2) * 64; vcol = 4992 + (head >> 2) * 64; }
;   __syncthreads();
;   {
;     const size_t pos = (size_t)r0 + (size_t)dil * (i0 + lrow);
;     const h16* g = P + pos * NSM + qcol + 16 * seg;
;     img_store_nat(Qi, lrow, seg, *(const u4v*)g, *(const u4v*)(g + 8));
;   }
;   float mrow[4], lsum[4];
;   f4v O[4];
;   float m_init = -1e30f, l_init = 0.f;
;   if (mode == 1) { m_init = p.d_sink[l * 8 + head]; l_init = 1.f; }
; #pragma unroll
;   for (int i = 0; i < 4; ++i) { mrow[i] = m_init; lsum[i] = l_init; O[i] = (f4v){0.f, 0.f, 0.f, 0.f}; }
;   u4v pk0, pk1, pv0, pv1;
;     ...
;   ATT_PREFETCH(0);
; DI void phase_m2(const Params& p, int l, int bid, int nb, h16* lds) {
;     ...
;     v -= 2048;
;     const int grp = v >> 10, x = v & 1023, head = x & 3, tl = x >> 2;
;     const int dil = (grp == 0) ? 1 : (grp == 1) ? 4 : 16;
;     const int sub = SEQ / dil, tps = sub >> 6;
;     const int res = tl / tps, ti = tl % tps;
;     attn_unit<3>(p, l, 0, grp, head, res, dil, ti * 64, sub, 64, lds);
.LBB0_897:
	s_movk_i32 s2, 0x14a8
	v_cmp_gt_i32_e32 vcc, s2, v1
	s_and_saveexec_b64 s[2:3], vcc
	s_xor_b64 s[84:85], exec, s[2:3]
	s_cbranch_execz .LBB0_960
	v_cmp_lt_i32_e32 vcc, 31, v1
	s_and_saveexec_b64 s[2:3], vcc
	s_xor_b64 s[86:87], exec, s[2:3]
	s_cbranch_execz .LBB0_953
	s_movk_i32 s2, 0xa7
	v_cmp_lt_u32_e32 vcc, s2, v1
	s_and_saveexec_b64 s[2:3], vcc
	s_xor_b64 s[88:89], exec, s[2:3]
	s_cbranch_execz .LBB0_915
	s_movk_i32 s2, 0x8a7
	v_cmp_lt_u32_e32 vcc, s2, v1
	s_and_saveexec_b64 s[2:3], vcc
	s_xor_b64 s[34:35], exec, s[2:3]
	s_cbranch_execz .LBB0_910
	v_readfirstlane_b32 s36, v1
	v_readfirstlane_b32 s58, v182
	s_lshr_b32 s58, s58, 6
	s_sub_u32 s51, s36, 0x8a8
	s_and_b32 s56, s51, 15
	s_sub_u32 s56, s56, 8
	s_and_b32 s56, s56, 15
	s_lshr_b32 s56, s56, 1
	s_lshr_b32 s57, s51, 4
	s_lshl_b32 s57, s57, 1
	s_and_b32 s59, s51, 1
	s_or_b32 s57, s57, s59
	s_mul_i32 s59, s57, 0xaaab
	s_lshr_b32 s59, s59, 19
	s_mul_i32 s62, s59, 12
	s_sub_u32 s62, s57, s62
	s_lshr_b32 s61, s62, 2
	s_and_b32 s37, s62, 3
	s_lshl_b32 s62, s56, 5
	s_add_u32 s62, s62, s59
	s_lshl_b32 s63, s61, 1
	s_lshl_b32 s60, 1, s63
	s_movk_i32 s39, 0x2800
	s_lshl_b32 s39, s39, s63
	s_movk_i32 s41, 0x4000
	s_lshr_b32 s41, s41, s63
	s_sub_u32 s51, 8, s63
	s_lshr_b32 s40, s62, s51
	s_movk_i32 s51, 0x100
	s_lshr_b32 s51, s51, s63
	s_sub_u32 s51, s51, 1
	s_and_b32 s38, s62, s51
	s_lshl_b32 s38, s38, 6
	s_lshl_b32 s51, s61, 9
	s_lshl_b32 s56, s37, 7
	s_add_u32 s51, s51, s56
	s_add_u32 s53, s51, 0x800
	s_add_u32 s54, s51, 0xe00
	s_add_u32 s55, s51, 0x1400
	v_and_b32_e32 v179, 63, v182
	v_and_b32_e32 v200, 15, v179
	v_lshrrev_b32_e32 v201, 4, v179
	v_lshlrev_b32_e32 v202, 4, v201
	v_mad_u32_u24 v2, v200, s39, v202
	v_add_u32_e32 v203, 16, v200
	v_mad_u32_u24 v3, v203, s39, v202
	v_add_u32_e32 v203, 32, v200
	v_mad_u32_u24 v4, v203, s39, v202
	v_add_u32_e32 v203, 48, v200
	v_mad_u32_u24 v5, v203, s39, v202
	s_lshl_b32 s51, s58, 4
	v_add_u32_e32 v203, s51, v200
	v_mad_u32_u24 v248, v203, s39, v202
	v_lshlrev_b32_e32 v160, 2, v201
	v_sub_u32_e32 v160, v160, v203
	s_lshl_b32 s51, s60, 9
	v_mul_u32_u24_e32 v249, s51, v203
	s_lshl_b32 s51, s60, 5
	v_mul_u32_u24_e32 v203, s51, v203
	v_lshl_add_u32 v249, v201, 3, v249
	v_lshrrev_b32_e32 v203, 3, v179
	s_lshl_b32 s51, s58, 4
	v_add_u32_e32 v203, s51, v203
	v_and_b32_e32 v202, 7, v179
	v_lshlrev_b32_e32 v202, 4, v202
	v_mad_u32_u24 v6, v203, s39, v202
	v_add_u32_e32 v200, 8, v203
	v_mad_u32_u24 v7, v200, s39, v202
	s_movk_i32 s57, 0x90
	v_mad_u32_u24 v158, v203, s57, v183
	v_add_u32_e32 v158, v158, v202
	v_and_b32_e32 v200, 15, v179
	v_mad_u32_u24 v8, v200, s57, v183
	v_lshl_add_u32 v8, v201, 4, v8
	v_lshrrev_b32_e32 v203, 2, v179
	v_mad_u32_u24 v159, v203, s57, v183
	v_and_b32_e32 v203, 3, v179
	v_lshl_add_u32 v159, v203, 3, v159
	v_add_u32_e32 v159, 0x2400, v159
	v_xor_b32_e32 v174, 16, v179
	v_lshlrev_b32_e32 v174, 2, v174
	v_xor_b32_e32 v175, 32, v179
	v_lshlrev_b32_e32 v175, 2, v175
	s_mul_i32 s51, s60, s38
	s_add_u32 s51, s51, s40
	s_mul_i32 s56, s51, 0x2800
	s_add_u32 s56, s56, s53
	s_add_u32 s42, s0, s56
	s_addc_u32 s43, s1, 0
	global_load_dwordx4 v[10:13], v248, s[42:43]
	global_load_dwordx4 v[14:17], v248, s[42:43] offset:64
	v_readlane_b32 s48, v254, 32
	v_readlane_b32 s49, v254, 33
	v_readlane_b32 s16, v254, 34
	v_readlane_b32 s17, v254, 35
	s_lshl_b32 s56, s61, 14
	s_add_u32 s56, s56, s51
	s_lshl_b32 s57, s56, 9
	s_lshl_b32 s59, s37, 7
	s_add_u32 s57, s57, s59
	s_add_u32 s48, s48, s57
	s_addc_u32 s49, s49, 0
	s_lshl_b32 s57, s56, 5
	s_lshl_b32 s59, s37, 3
	s_add_u32 s57, s57, s59
	s_add_u32 s16, s16, s57
	s_addc_u32 s17, s17, 0
	v_mov_b32_e32 v176, 0xf149f2ca
	v_mov_b32_e32 v177, 0
	v_mov_b32_e32 v138, 0
	v_mov_b32_e32 v139, 0
	v_mov_b32_e32 v140, 0
	v_mov_b32_e32 v141, 0
	v_mov_b32_e32 v142, 0
	v_mov_b32_e32 v143, 0
	v_mov_b32_e32 v144, 0
	v_mov_b32_e32 v145, 0
	v_mov_b32_e32 v146, 0
	v_mov_b32_e32 v147, 0
	v_mov_b32_e32 v148, 0
	v_mov_b32_e32 v149, 0
	v_mov_b32_e32 v150, 0
	v_mov_b32_e32 v151, 0
	v_mov_b32_e32 v152, 0
	v_mov_b32_e32 v153, 0
	s_sub_u32 s50, s38, 64
	s_cmp_ge_i32 s50, 0
	s_cselect_b32 s56, 1, 0
	s_cmp_lt_i32 s50, s41
	s_cselect_b32 s57, 1, 0
	s_and_b32 s2, s56, s57
	s_cmp_eq_u32 s2, 1
	s_cselect_b32 s50, s50, s38
	s_mul_i32 s50, s50, s60
	s_add_u32 s50, s50, s40
	s_mul_i32 s50, s50, 0x2800
	s_add_u32 s56, s50, s54
	s_add_u32 s44, s0, s56
	s_addc_u32 s45, s1, 0
	s_add_u32 s56, s50, s55
	s_add_u32 s46, s0, s56
	s_addc_u32 s47, s1, 0
	global_load_dwordx4 v[50:53], v6, s[44:45]
	global_load_dwordx4 v[54:57], v7, s[44:45]
	global_load_dwordx4 v[58:61], v6, s[46:47]
	global_load_dwordx4 v[62:65], v7, s[46:47]
	s_add_u32 s50, s38, 0
	s_cmp_ge_i32 s50, 0
	s_cselect_b32 s56, 1, 0
	s_cmp_lt_i32 s50, s41
	s_cselect_b32 s57, 1, 0
	s_and_b32 s3, s56, s57
	s_cmp_eq_u32 s3, 1
	s_cselect_b32 s50, s50, s38
	s_mul_i32 s50, s50, s60
	s_add_u32 s50, s50, s40
	s_mul_i32 s50, s50, 0x2800
	s_add_u32 s56, s50, s54
	s_add_u32 s44, s0, s56
	s_addc_u32 s45, s1, 0
	s_add_u32 s56, s50, s55
	s_add_u32 s46, s0, s56
	s_addc_u32 s47, s1, 0
	global_load_dwordx4 v[66:69], v6, s[44:45]
	global_load_dwordx4 v[70:73], v7, s[44:45]
	global_load_dwordx4 v[74:77], v6, s[46:47]
	global_load_dwordx4 v[78:81], v7, s[46:47]
	s_waitcnt vmcnt(4)
	ds_write_b128 v158, v[50:53] offset:0
	ds_write_b128 v158, v[54:57] offset:1152
	ds_write_b128 v158, v[58:61] offset:9216
	ds_write_b128 v158, v[62:65] offset:10368
	s_waitcnt lgkmcnt(0)
	s_barrier
; DI float grp16_max(float v) { v = fmaxf(v, __shfl_xor(v, 1)); v = fmaxf(v, __shfl_xor(v, 2)); v = fmaxf(v, __shfl_xor(v, 4)); v = fmaxf(v, __shfl_xor(v, 8)); return v; }
; template <int NKB>
; DI void attn_unit(const Params& p, int l, int mode, int grp, int head, int r0, int dil, int i0, int sub_len, int W, h16* lds) {
;     ...
;   for (int kb = 0; kb < NKB; ++kb) {
;     const int j0 = i0 - W + 64 * kb;
;     const bool inr = (j0 >= 0) && (j0 < sub_len);
;     __syncthreads();
;     img_store_nat(Ki, lrow, seg, pk0, pk1);
;     img_store_T(Vt, lrow, seg, pv0, pv1);
;     __syncthreads();
;     if (kb + 1 < NKB) ATT_PREFETCH(kb + 1);
;     f4v S[4];
; #pragma unroll
;     for (int i = 0; i < 4; ++i) S[i] = (f4v){0.f, 0.f, 0.f, 0.f};
;     mm64(Qi, Ki, S, w, lane);
;     float mx[4], al[4], rsum[4];
;     bool vm[4][4];
; #pragma unroll
;     for (int rg = 0; rg < 4; ++rg) {
;       const int row = 16 * w + 4 * q + rg;
;       float m_ = -1e30f;
; #pragma unroll
;       for (int nt = 0; nt < 4; ++nt) {
;         const int key = 16 * nt + r;
;         const int delta = row - key + W - 64 * kb;
;         const bool ok = inr && (delta >= -W) && (delta <= W);
;         vm[nt][rg] = ok;
;         float s = S[nt][rg] * 0.125f;
;         S[nt][rg] = s;
;         if (ok) m_ = fmaxf(m_, s);
;       }
;       mx[rg] = grp16_max(m_);
;     }
	s_add_u32 s50, s38, 64
	s_cmp_ge_i32 s50, 0
	s_cselect_b32 s56, 1, 0
	s_cmp_lt_i32 s50, s41
	s_cselect_b32 s57, 1, 0
	s_and_b32 s4, s56, s57
	s_cmp_eq_u32 s4, 1
	s_cselect_b32 s50, s50, s38
	s_mul_i32 s50, s50, s60
	s_add_u32 s50, s50, s40
	s_mul_i32 s50, s50, 0x2800
	s_add_u32 s56, s50, s54
	s_add_u32 s44, s0, s56
	s_addc_u32 s45, s1, 0
	s_add_u32 s56, s50, s55
	s_add_u32 s46, s0, s56
	s_addc_u32 s47, s1, 0
	global_load_dwordx4 v[50:53], v6, s[44:45]
	global_load_dwordx4 v[54:57], v7, s[44:45]
	global_load_dwordx4 v[58:61], v6, s[46:47]
	global_load_dwordx4 v[62:65], v7, s[46:47]
	s_cmp_eq_u32 s2, 1
	s_cbranch_scc0 .Lat0_kb0_end
	ds_read_b128 v[18:21], v8 offset:0
	ds_read_b128 v[22:25], v8 offset:64
	ds_read_b128 v[26:29], v8 offset:2304
	ds_read_b128 v[30:33], v8 offset:2368
	ds_read_b128 v[34:37], v8 offset:4608
	ds_read_b128 v[38:41], v8 offset:4672
	ds_read_b128 v[42:45], v8 offset:6912
	ds_read_b128 v[46:49], v8 offset:6976
	ds_read_b64_tr_b16 v[216:217], v159
	ds_read_b64_tr_b16 v[218:219], v159 offset:2304
	ds_read_b64_tr_b16 v[220:221], v159 offset:4608
	ds_read_b64_tr_b16 v[222:223], v159 offset:6912
	ds_read_b64_tr_b16 v[224:225], v159 offset:32
	ds_read_b64_tr_b16 v[226:227], v159 offset:2336
	ds_read_b64_tr_b16 v[228:229], v159 offset:4640
	ds_read_b64_tr_b16 v[230:231], v159 offset:6944
	ds_read_b64_tr_b16 v[232:233], v159 offset:64
	ds_read_b64_tr_b16 v[234:235], v159 offset:2368
	ds_read_b64_tr_b16 v[236:237], v159 offset:4672
	ds_read_b64_tr_b16 v[238:239], v159 offset:6976
	ds_read_b64_tr_b16 v[240:241], v159 offset:96
	ds_read_b64_tr_b16 v[242:243], v159 offset:2400
	ds_read_b64_tr_b16 v[244:245], v159 offset:4704
	ds_read_b64_tr_b16 v[246:247], v159 offset:7008
	s_waitcnt lgkmcnt(15)
	v_mfma_f32_16x16x32_f16 v[114:117], v[18:21], v[10:13], 0
	v_mfma_f32_16x16x32_f16 v[118:121], v[26:29], v[10:13], 0
	v_mfma_f32_16x16x32_f16 v[122:125], v[34:37], v[10:13], 0
	v_mfma_f32_16x16x32_f16 v[126:129], v[42:45], v[10:13], 0
	v_mfma_f32_16x16x32_f16 v[114:117], v[22:25], v[14:17], v[114:117]
	v_mfma_f32_16x16x32_f16 v[118:121], v[30:33], v[14:17], v[118:121]
	v_mfma_f32_16x16x32_f16 v[122:125], v[38:41], v[14:17], v[122:125]
	v_mfma_f32_16x16x32_f16 v[126:129], v[46:49], v[14:17], v[126:129]
	s_nop 7
	s_nop 7
	v_mul_f32_e32 v114, 0x3e000000, v114
	v_mul_f32_e32 v115, 0x3e000000, v115
	v_mul_f32_e32 v116, 0x3e000000, v116
	v_mul_f32_e32 v117, 0x3e000000, v117
	v_mul_f32_e32 v118, 0x3e000000, v118
	v_mul_f32_e32 v119, 0x3e000000, v119
	v_mul_f32_e32 v120, 0x3e000000, v120
	v_mul_f32_e32 v121, 0x3e000000, v121
	v_mul_f32_e32 v122, 0x3e000000, v122
	v_mul_f32_e32 v123, 0x3e000000, v123
	v_mul_f32_e32 v124, 0x3e000000, v124
	v_mul_f32_e32 v125, 0x3e000000, v125
	v_mul_f32_e32 v126, 0x3e000000, v126
	v_mul_f32_e32 v127, 0x3e000000, v127
	v_mul_f32_e32 v128, 0x3e000000, v128
	v_mul_f32_e32 v129, 0x3e000000, v129
	v_mov_b32_e32 v200, 0xf149f2ca
	v_cmp_le_i32_e32 vcc, 0, v160
	v_cndmask_b32_e32 v114, v200, v114, vcc
	v_cmp_le_i32_e32 vcc, -1, v160
	v_cndmask_b32_e32 v115, v200, v115, vcc
	v_cmp_le_i32_e32 vcc, -2, v160
	v_cndmask_b32_e32 v116, v200, v116, vcc
	v_cmp_le_i32_e32 vcc, -3, v160
	v_cndmask_b32_e32 v117, v200, v117, vcc
	v_cmp_le_i32_e32 vcc, -16, v160
	v_cndmask_b32_e32 v118, v200, v118, vcc
	v_cmp_le_i32_e32 vcc, -17, v160
	v_cndmask_b32_e32 v119, v200, v119, vcc
	v_cmp_le_i32_e32 vcc, -18, v160
	v_cndmask_b32_e32 v120, v200, v120, vcc
	v_cmp_le_i32_e32 vcc, -19, v160
	v_cndmask_b32_e32 v121, v200, v121, vcc
	v_cmp_le_i32_e32 vcc, -32, v160
	v_cndmask_b32_e32 v122, v200, v122, vcc
	v_cmp_le_i32_e32 vcc, -33, v160
	v_cndmask_b32_e32 v123, v200, v123, vcc
	v_cmp_le_i32_e32 vcc, -34, v160
	v_cndmask_b32_e32 v124, v200, v124, vcc
	v_cmp_le_i32_e32 vcc, -35, v160
	v_cndmask_b32_e32 v125, v200, v125, vcc
	v_cmp_le_i32_e32 vcc, -48, v160
	v_cndmask_b32_e32 v126, v200, v126, vcc
	v_cmp_le_i32_e32 vcc, -49, v160
	v_cndmask_b32_e32 v127, v200, v127, vcc
	v_cmp_le_i32_e32 vcc, -50, v160
	v_cndmask_b32_e32 v128, v200, v128, vcc
	v_cmp_le_i32_e32 vcc, -51, v160
	v_cndmask_b32_e32 v129, v200, v129, vcc
	v_max3_f32 v179, v114, v115, v116
	v_max3_f32 v179, v179, v117, v118
	v_max3_f32 v179, v179, v119, v120
	v_max3_f32 v179, v179, v121, v122
	v_max3_f32 v179, v179, v123, v124
	v_max3_f32 v179, v179, v125, v126
	v_max3_f32 v179, v179, v127, v128
	v_max_f32_e32 v179, v179, v129
	ds_bpermute_b32 v201, v174, v179
	s_waitcnt lgkmcnt(0)
	v_max_f32_e32 v179, v179, v201
	ds_bpermute_b32 v201, v175, v179
	s_waitcnt lgkmcnt(0)
; DI float grp16_sum(float v) { v += __shfl_xor(v, 1); v += __shfl_xor(v, 2); v += __shfl_xor(v, 4); v += __shfl_xor(v, 8); return v; }
; template <int NKB>
; DI void attn_unit(const Params& p, int l, int mode, int grp, int head, int r0, int dil, int i0, int sub_len, int W, h16* lds) {
;     ...
; #pragma unroll
;     for (int rg = 0; rg < 4; ++rg) {
;       const float mn = fmaxf(mrow[rg], mx[rg]);
;       al[rg] = __expf(mrow[rg] - mn);
;       mrow[rg] = mn;
;       float rs_ = 0.f;
; #pragma unroll
;       for (int nt = 0; nt < 4; ++nt) {
;         float pv = vm[nt][rg] ? __expf(S[nt][rg] - mn) : 0.f;
;         rs_ += pv;
;         Pi[(16 * w + 4 * q + rg) * LDH + 16 * nt + r] = (h16)pv;
;       }
;       rsum[rg] = grp16_sum(rs_);
;       lsum[rg] = lsum[rg] * al[rg] + rsum[rg];
;     }
; #pragma unroll
;     for (int et = 0; et < 4; ++et)
; #pragma unroll
;       for (int rg = 0; rg < 4; ++rg) O[et][rg] *= al[rg];
;     __syncthreads();
;     mm64(Pi, Vt, O, w, lane);
;   }
	v_max3_f32 v179, v179, v201, v176
	v_sub_f32_e32 v178, v176, v179
	v_mul_f32_e32 v178, 0x3fb8aa3b, v178
	v_exp_f32_e32 v178, v178
	v_mov_b32_e32 v176, v179
	v_mul_f32_e32 v202, 0xbfb8aa3b, v179
	v_mov_b32_e32 v203, 0x3fb8aa3b
	v_fma_f32 v114, v114, v203, v202
	v_fma_f32 v115, v115, v203, v202
	v_fma_f32 v116, v116, v203, v202
	v_fma_f32 v117, v117, v203, v202
	v_fma_f32 v118, v118, v203, v202
	v_fma_f32 v119, v119, v203, v202
	v_fma_f32 v120, v120, v203, v202
	v_fma_f32 v121, v121, v203, v202
	v_fma_f32 v122, v122, v203, v202
	v_fma_f32 v123, v123, v203, v202
	v_fma_f32 v124, v124, v203, v202
	v_fma_f32 v125, v125, v203, v202
	v_fma_f32 v126, v126, v203, v202
	v_fma_f32 v127, v127, v203, v202
	v_fma_f32 v128, v128, v203, v202
	v_fma_f32 v129, v129, v203, v202
	v_exp_f32_e32 v114, v114
	v_exp_f32_e32 v115, v115
	v_exp_f32_e32 v116, v116
	v_exp_f32_e32 v117, v117
	v_exp_f32_e32 v118, v118
	v_exp_f32_e32 v119, v119
	v_exp_f32_e32 v120, v120
	v_exp_f32_e32 v121, v121
	v_exp_f32_e32 v122, v122
	v_exp_f32_e32 v123, v123
	v_exp_f32_e32 v124, v124
	v_exp_f32_e32 v125, v125
	v_exp_f32_e32 v126, v126
	v_exp_f32_e32 v127, v127
	v_exp_f32_e32 v128, v128
	v_exp_f32_e32 v129, v129
	s_nop 0
	v_fma_f32 v177, v177, v178, v114
	v_add_f32_e32 v177, v177, v115
	v_add_f32_e32 v177, v177, v116
	v_add_f32_e32 v177, v177, v117
	v_add_f32_e32 v177, v177, v118
	v_add_f32_e32 v177, v177, v119
	v_add_f32_e32 v177, v177, v120
	v_add_f32_e32 v177, v177, v121
	v_add_f32_e32 v177, v177, v122
	v_add_f32_e32 v177, v177, v123
	v_add_f32_e32 v177, v177, v124
	v_add_f32_e32 v177, v177, v125
	v_add_f32_e32 v177, v177, v126
	v_add_f32_e32 v177, v177, v127
	v_add_f32_e32 v177, v177, v128
	v_add_f32_e32 v177, v177, v129
	v_cvt_pk_f16_f32 v130, v114, v115
	v_cvt_pk_f16_f32 v131, v116, v117
	v_cvt_pk_f16_f32 v132, v118, v119
	v_cvt_pk_f16_f32 v133, v120, v121
	v_cvt_pk_f16_f32 v134, v122, v123
	v_cvt_pk_f16_f32 v135, v124, v125
	v_cvt_pk_f16_f32 v136, v126, v127
	v_cvt_pk_f16_f32 v137, v128, v129
	v_pk_mul_f32 v[138:139], v[138:139], v[178:179] op_sel_hi:[1,0]
	v_pk_mul_f32 v[140:141], v[140:141], v[178:179] op_sel_hi:[1,0]
	v_pk_mul_f32 v[142:143], v[142:143], v[178:179] op_sel_hi:[1,0]
	v_pk_mul_f32 v[144:145], v[144:145], v[178:179] op_sel_hi:[1,0]
	v_pk_mul_f32 v[146:147], v[146:147], v[178:179] op_sel_hi:[1,0]
	v_pk_mul_f32 v[148:149], v[148:149], v[178:179] op_sel_hi:[1,0]
	v_pk_mul_f32 v[150:151], v[150:151], v[178:179] op_sel_hi:[1,0]
	v_pk_mul_f32 v[152:153], v[152:153], v[178:179] op_sel_hi:[1,0]
	s_nop 1
	v_mfma_f32_16x16x32_f16 v[138:141], v[216:219], v[130:133], v[138:141]
	v_mfma_f32_16x16x32_f16 v[142:145], v[224:227], v[130:133], v[142:145]
	v_mfma_f32_16x16x32_f16 v[146:149], v[232:235], v[130:133], v[146:149]
	v_mfma_f32_16x16x32_f16 v[150:153], v[240:243], v[130:133], v[150:153]
	v_mfma_f32_16x16x32_f16 v[138:141], v[220:223], v[134:137], v[138:141]
	v_mfma_f32_16x16x32_f16 v[142:145], v[228:231], v[134:137], v[142:145]
	v_mfma_f32_16x16x32_f16 v[146:149], v[236:239], v[134:137], v[146:149]
	v_mfma_f32_16x16x32_f16 v[150:153], v[244:247], v[134:137], v[150:153]
.Lat0_kb0_end:
	s_waitcnt vmcnt(4)
	ds_write_b128 v158, v[66:69] offset:18432
	ds_write_b128 v158, v[70:73] offset:19584
	ds_write_b128 v158, v[74:77] offset:27648
	ds_write_b128 v158, v[78:81] offset:28800
	s_waitcnt lgkmcnt(0)
	s_barrier
	s_cmp_eq_u32 s3, 1
	s_cbranch_scc0 .Lat0_kb1_end
	ds_read_b128 v[18:21], v8 offset:18432
	ds_read_b128 v[22:25], v8 offset:18496
	ds_read_b128 v[26:29], v8 offset:20736
	ds_read_b128 v[30:33], v8 offset:20800
	ds_read_b128 v[34:37], v8 offset:23040
	ds_read_b128 v[38:41], v8 offset:23104
	ds_read_b128 v[42:45], v8 offset:25344
	ds_read_b128 v[46:49], v8 offset:25408
	ds_read_b64_tr_b16 v[216:217], v159 offset:18432
	ds_read_b64_tr_b16 v[218:219], v159 offset:20736
	ds_read_b64_tr_b16 v[220:221], v159 offset:23040
	ds_read_b64_tr_b16 v[222:223], v159 offset:25344
	ds_read_b64_tr_b16 v[224:225], v159 offset:18464
	ds_read_b64_tr_b16 v[226:227], v159 offset:20768
	ds_read_b64_tr_b16 v[228:229], v159 offset:23072
	ds_read_b64_tr_b16 v[230:231], v159 offset:25376
	ds_read_b64_tr_b16 v[232:233], v159 offset:18496
	ds_read_b64_tr_b16 v[234:235], v159 offset:20800
	ds_read_b64_tr_b16 v[236:237], v159 offset:23104
	ds_read_b64_tr_b16 v[238:239], v159 offset:25408
	ds_read_b64_tr_b16 v[240:241], v159 offset:18528
	ds_read_b64_tr_b16 v[242:243], v159 offset:20832
	ds_read_b64_tr_b16 v[244:245], v159 offset:23136
	ds_read_b64_tr_b16 v[246:247], v159 offset:25440
	s_waitcnt lgkmcnt(15)
	v_mfma_f32_16x16x32_f16 v[114:117], v[18:21], v[10:13], 0
	v_mfma_f32_16x16x32_f16 v[118:121], v[26:29], v[10:13], 0
	v_mfma_f32_16x16x32_f16 v[122:125], v[34:37], v[10:13], 0
	v_mfma_f32_16x16x32_f16 v[126:129], v[42:45], v[10:13], 0
	v_mfma_f32_16x16x32_f16 v[114:117], v[22:25], v[14:17], v[114:117]
	v_mfma_f32_16x16x32_f16 v[118:121], v[30:33], v[14:17], v[118:121]
	v_mfma_f32_16x16x32_f16 v[122:125], v[38:41], v[14:17], v[122:125]
	v_mfma_f32_16x16x32_f16 v[126:129], v[46:49], v[14:17], v[126:129]
	s_nop 7
	s_nop 7
	v_mul_f32_e32 v114, 0x3e000000, v114
	v_mul_f32_e32 v115, 0x3e000000, v115
	v_mul_f32_e32 v116, 0x3e000000, v116
	v_mul_f32_e32 v117, 0x3e000000, v117
	v_mul_f32_e32 v118, 0x3e000000, v118
	v_mul_f32_e32 v119, 0x3e000000, v119
	v_mul_f32_e32 v120, 0x3e000000, v120
	v_mul_f32_e32 v121, 0x3e000000, v121
	v_mul_f32_e32 v122, 0x3e000000, v122
	v_mul_f32_e32 v123, 0x3e000000, v123
	v_mul_f32_e32 v124, 0x3e000000, v124
	v_mul_f32_e32 v125, 0x3e000000, v125
	v_mul_f32_e32 v126, 0x3e000000, v126
	v_mul_f32_e32 v127, 0x3e000000, v127
	v_mul_f32_e32 v128, 0x3e000000, v128
	v_mul_f32_e32 v129, 0x3e000000, v129
	v_max3_f32 v179, v114, v115, v116
	v_max3_f32 v179, v179, v117, v118
	v_max3_f32 v179, v179, v119, v120
	v_max3_f32 v179, v179, v121, v122
	v_max3_f32 v179, v179, v123, v124
	v_max3_f32 v179, v179, v125, v126
	v_max3_f32 v179, v179, v127, v128
	v_max_f32_e32 v179, v179, v129
	ds_bpermute_b32 v201, v174, v179
	s_waitcnt lgkmcnt(0)
; DI float grp16_sum(float v) { v += __shfl_xor(v, 1); v += __shfl_xor(v, 2); v += __shfl_xor(v, 4); v += __shfl_xor(v, 8); return v; }
; DI float grp16_max(float v) { v = fmaxf(v, __shfl_xor(v, 1)); v = fmaxf(v, __shfl_xor(v, 2)); v = fmaxf(v, __shfl_xor(v, 4)); v = fmaxf(v, __shfl_xor(v, 8)); return v; }
; template <int NKB>
; DI void attn_unit(const Params& p, int l, int mode, int grp, int head, int r0, int dil, int i0, int sub_len, int W, h16* lds) {
;     ...
;   for (int kb = 0; kb < NKB; ++kb) {
;     const int j0 = i0 - W + 64 * kb;
;     const bool inr = (j0 >= 0) && (j0 < sub_len);
;     __syncthreads();
;     img_store_nat(Ki, lrow, seg, pk0, pk1);
;     img_store_T(Vt, lrow, seg, pv0, pv1);
;     __syncthreads();
;     if (kb + 1 < NKB) ATT_PREFETCH(kb + 1);
;     f4v S[4];
; #pragma unroll
;     for (int i = 0; i < 4; ++i) S[i] = (f4v){0.f, 0.f, 0.f, 0.f};
;     mm64(Qi, Ki, S, w, lane);
;     float mx[4], al[4], rsum[4];
;     bool vm[4][4];
; #pragma unroll
;     for (int rg = 0; rg < 4; ++rg) {
;       const int row = 16 * w + 4 * q + rg;
;       float m_ = -1e30f;
; #pragma unroll
;       for (int nt = 0; nt < 4; ++nt) {
;         const int key = 16 * nt + r;
;         const int delta = row - key + W - 64 * kb;
;         const bool ok = inr && (delta >= -W) && (delta <= W);
;         vm[nt][rg] = ok;
;         float s = S[nt][rg] * 0.125f;
;         S[nt][rg] = s;
;         if (ok) m_ = fmaxf(m_, s);
;       }
;       mx[rg] = grp16_max(m_);
;     }
; #pragma unroll
;     for (int rg = 0; rg < 4; ++rg) {
;       const float mn = fmaxf(mrow[rg], mx[rg]);
;       al[rg] = __expf(mrow[rg] - mn);
;       mrow[rg] = mn;
;       float rs_ = 0.f;
; #pragma unroll
;       for (int nt = 0; nt < 4; ++nt) {
;         float pv = vm[nt][rg] ? __expf(S[nt][rg] - mn) : 0.f;
;         rs_ += pv;
;         Pi[(16 * w + 4 * q + rg) * LDH + 16 * nt + r] = (h16)pv;
;       }
;       rsum[rg] = grp16_sum(rs_);
;       lsum[rg] = lsum[rg] * al[rg] + rsum[rg];
;     }
; #pragma unroll
;     for (int et = 0; et < 4; ++et)
; #pragma unroll
;       for (int rg = 0; rg < 4; ++rg) O[et][rg] *= al[rg];
;     __syncthreads();
;     mm64(Pi, Vt, O, w, lane);
;   }
	v_max_f32_e32 v179, v179, v201
	ds_bpermute_b32 v201, v175, v179
	s_waitcnt lgkmcnt(0)
	v_max3_f32 v179, v179, v201, v176
	v_sub_f32_e32 v178, v176, v179
	v_mul_f32_e32 v178, 0x3fb8aa3b, v178
	v_exp_f32_e32 v178, v178
	v_mov_b32_e32 v176, v179
	v_mul_f32_e32 v202, 0xbfb8aa3b, v179
	v_mov_b32_e32 v203, 0x3fb8aa3b
	v_fma_f32 v114, v114, v203, v202
	v_fma_f32 v115, v115, v203, v202
	v_fma_f32 v116, v116, v203, v202
	v_fma_f32 v117, v117, v203, v202
	v_fma_f32 v118, v118, v203, v202
	v_fma_f32 v119, v119, v203, v202
	v_fma_f32 v120, v120, v203, v202
	v_fma_f32 v121, v121, v203, v202
	v_fma_f32 v122, v122, v203, v202
	v_fma_f32 v123, v123, v203, v202
	v_fma_f32 v124, v124, v203, v202
	v_fma_f32 v125, v125, v203, v202
	v_fma_f32 v126, v126, v203, v202
	v_fma_f32 v127, v127, v203, v202
	v_fma_f32 v128, v128, v203, v202
	v_fma_f32 v129, v129, v203, v202
	v_exp_f32_e32 v114, v114
	v_exp_f32_e32 v115, v115
	v_exp_f32_e32 v116, v116
	v_exp_f32_e32 v117, v117
	v_exp_f32_e32 v118, v118
	v_exp_f32_e32 v119, v119
	v_exp_f32_e32 v120, v120
	v_exp_f32_e32 v121, v121
	v_exp_f32_e32 v122, v122
	v_exp_f32_e32 v123, v123
	v_exp_f32_e32 v124, v124
	v_exp_f32_e32 v125, v125
	v_exp_f32_e32 v126, v126
	v_exp_f32_e32 v127, v127
	v_exp_f32_e32 v128, v128
	v_exp_f32_e32 v129, v129
	s_nop 0
	v_fma_f32 v177, v177, v178, v114
	v_add_f32_e32 v177, v177, v115
	v_add_f32_e32 v177, v177, v116
	v_add_f32_e32 v177, v177, v117
	v_add_f32_e32 v177, v177, v118
	v_add_f32_e32 v177, v177, v119
	v_add_f32_e32 v177, v177, v120
	v_add_f32_e32 v177, v177, v121
	v_add_f32_e32 v177, v177, v122
	v_add_f32_e32 v177, v177, v123
	v_add_f32_e32 v177, v177, v124
	v_add_f32_e32 v177, v177, v125
	v_add_f32_e32 v177, v177, v126
	v_add_f32_e32 v177, v177, v127
	v_add_f32_e32 v177, v177, v128
	v_add_f32_e32 v177, v177, v129
	v_cvt_pk_f16_f32 v130, v114, v115
	v_cvt_pk_f16_f32 v131, v116, v117
	v_cvt_pk_f16_f32 v132, v118, v119
	v_cvt_pk_f16_f32 v133, v120, v121
	v_cvt_pk_f16_f32 v134, v122, v123
	v_cvt_pk_f16_f32 v135, v124, v125
	v_cvt_pk_f16_f32 v136, v126, v127
	v_cvt_pk_f16_f32 v137, v128, v129
	v_pk_mul_f32 v[138:139], v[138:139], v[178:179] op_sel_hi:[1,0]
	v_pk_mul_f32 v[140:141], v[140:141], v[178:179] op_sel_hi:[1,0]
	v_pk_mul_f32 v[142:143], v[142:143], v[178:179] op_sel_hi:[1,0]
	v_pk_mul_f32 v[144:145], v[144:145], v[178:179] op_sel_hi:[1,0]
	v_pk_mul_f32 v[146:147], v[146:147], v[178:179] op_sel_hi:[1,0]
	v_pk_mul_f32 v[148:149], v[148:149], v[178:179] op_sel_hi:[1,0]
	v_pk_mul_f32 v[150:151], v[150:151], v[178:179] op_sel_hi:[1,0]
	v_pk_mul_f32 v[152:153], v[152:153], v[178:179] op_sel_hi:[1,0]
	s_nop 1
	v_mfma_f32_16x16x32_f16 v[138:141], v[216:219], v[130:133], v[138:141]
	v_mfma_f32_16x16x32_f16 v[142:145], v[224:227], v[130:133], v[142:145]
	v_mfma_f32_16x16x32_f16 v[146:149], v[232:235], v[130:133], v[146:149]
	v_mfma_f32_16x16x32_f16 v[150:153], v[240:243], v[130:133], v[150:153]
	v_mfma_f32_16x16x32_f16 v[138:141], v[220:223], v[134:137], v[138:141]
	v_mfma_f32_16x16x32_f16 v[142:145], v[228:231], v[134:137], v[142:145]
	v_mfma_f32_16x16x32_f16 v[146:149], v[236:239], v[134:137], v[146:149]
	v_mfma_f32_16x16x32_f16 v[150:153], v[244:247], v[134:137], v[150:153]
.Lat0_kb1_end:
	s_waitcnt vmcnt(0)
	ds_write_b128 v158, v[50:53] offset:36864
	ds_write_b128 v158, v[54:57] offset:38016
	ds_write_b128 v158, v[58:61] offset:46080
	ds_write_b128 v158, v[62:65] offset:47232
	s_waitcnt lgkmcnt(0)
	s_barrier
	s_cmp_eq_u32 s4, 1
	s_cbranch_scc0 .Lat0_kb2_end
	ds_read_b128 v[18:21], v8 offset:36864
	ds_read_b128 v[22:25], v8 offset:36928
	ds_read_b128 v[26:29], v8 offset:39168
	ds_read_b128 v[30:33], v8 offset:39232
	ds_read_b128 v[34:37], v8 offset:41472
	ds_read_b128 v[38:41], v8 offset:41536
	ds_read_b128 v[42:45], v8 offset:43776
	ds_read_b128 v[46:49], v8 offset:43840
	ds_read_b64_tr_b16 v[216:217], v159 offset:36864
	ds_read_b64_tr_b16 v[218:219], v159 offset:39168
	ds_read_b64_tr_b16 v[220:221], v159 offset:41472
	ds_read_b64_tr_b16 v[222:223], v159 offset:43776
	ds_read_b64_tr_b16 v[224:225], v159 offset:36896
	ds_read_b64_tr_b16 v[226:227], v159 offset:39200
	ds_read_b64_tr_b16 v[228:229], v159 offset:41504
	ds_read_b64_tr_b16 v[230:231], v159 offset:43808
	ds_read_b64_tr_b16 v[232:233], v159 offset:36928
	ds_read_b64_tr_b16 v[234:235], v159 offset:39232
	ds_read_b64_tr_b16 v[236:237], v159 offset:41536
	ds_read_b64_tr_b16 v[238:239], v159 offset:43840
	ds_read_b64_tr_b16 v[240:241], v159 offset:36960
	ds_read_b64_tr_b16 v[242:243], v159 offset:39264
	ds_read_b64_tr_b16 v[244:245], v159 offset:41568
	ds_read_b64_tr_b16 v[246:247], v159 offset:43872
	s_waitcnt lgkmcnt(15)
; DI float grp16_sum(float v) { v += __shfl_xor(v, 1); v += __shfl_xor(v, 2); v += __shfl_xor(v, 4); v += __shfl_xor(v, 8); return v; }
; DI float grp16_max(float v) { v = fmaxf(v, __shfl_xor(v, 1)); v = fmaxf(v, __shfl_xor(v, 2)); v = fmaxf(v, __shfl_xor(v, 4)); v = fmaxf(v, __shfl_xor(v, 8)); return v; }
; template <int NKB>
; DI void attn_unit(const Params& p, int l, int mode, int grp, int head, int r0, int dil, int i0, int sub_len, int W, h16* lds) {
;     ...
;     float mx[4], al[4], rsum[4];
;     bool vm[4][4];
; #pragma unroll
;     for (int rg = 0; rg < 4; ++rg) {
;       const int row = 16 * w + 4 * q + rg;
;       float m_ = -1e30f;
; #pragma unroll
;       for (int nt = 0; nt < 4; ++nt) {
;         const int key = 16 * nt + r;
;         const int delta = row - key + W - 64 * kb;
;         const bool ok = inr && (delta >= -W) && (delta <= W);
;         vm[nt][rg] = ok;
;         float s = S[nt][rg] * 0.125f;
;         S[nt][rg] = s;
;         if (ok) m_ = fmaxf(m_, s);
;       }
;       mx[rg] = grp16_max(m_);
;     }
; #pragma unroll
;     for (int rg = 0; rg < 4; ++rg) {
;       const float mn = fmaxf(mrow[rg], mx[rg]);
;       al[rg] = __expf(mrow[rg] - mn);
;       mrow[rg] = mn;
;       float rs_ = 0.f;
; #pragma unroll
;       for (int nt = 0; nt < 4; ++nt) {
;         float pv = vm[nt][rg] ? __expf(S[nt][rg] - mn) : 0.f;
;         rs_ += pv;
;         Pi[(16 * w + 4 * q + rg) * LDH + 16 * nt + r] = (h16)pv;
;       }
;       rsum[rg] = grp16_sum(rs_);
;       lsum[rg] = lsum[rg] * al[rg] + rsum[rg];
;     }
; #pragma unroll
;     for (int et = 0; et < 4; ++et)
; #pragma unroll
;       for (int rg = 0; rg < 4; ++rg) O[et][rg] *= al[rg];
;     __syncthreads();
;     mm64(Pi, Vt, O, w, lane);
;   }
	v_mfma_f32_16x16x32_f16 v[114:117], v[18:21], v[10:13], 0
	v_mfma_f32_16x16x32_f16 v[118:121], v[26:29], v[10:13], 0
	v_mfma_f32_16x16x32_f16 v[122:125], v[34:37], v[10:13], 0
	v_mfma_f32_16x16x32_f16 v[126:129], v[42:45], v[10:13], 0
	v_mfma_f32_16x16x32_f16 v[114:117], v[22:25], v[14:17], v[114:117]
	v_mfma_f32_16x16x32_f16 v[118:121], v[30:33], v[14:17], v[118:121]
	v_mfma_f32_16x16x32_f16 v[122:125], v[38:41], v[14:17], v[122:125]
	v_mfma_f32_16x16x32_f16 v[126:129], v[46:49], v[14:17], v[126:129]
	s_nop 7
	s_nop 7
	v_mul_f32_e32 v114, 0x3e000000, v114
	v_mul_f32_e32 v115, 0x3e000000, v115
	v_mul_f32_e32 v116, 0x3e000000, v116
	v_mul_f32_e32 v117, 0x3e000000, v117
	v_mul_f32_e32 v118, 0x3e000000, v118
	v_mul_f32_e32 v119, 0x3e000000, v119
	v_mul_f32_e32 v120, 0x3e000000, v120
	v_mul_f32_e32 v121, 0x3e000000, v121
	v_mul_f32_e32 v122, 0x3e000000, v122
	v_mul_f32_e32 v123, 0x3e000000, v123
	v_mul_f32_e32 v124, 0x3e000000, v124
	v_mul_f32_e32 v125, 0x3e000000, v125
	v_mul_f32_e32 v126, 0x3e000000, v126
	v_mul_f32_e32 v127, 0x3e000000, v127
	v_mul_f32_e32 v128, 0x3e000000, v128
	v_mul_f32_e32 v129, 0x3e000000, v129
	v_mov_b32_e32 v200, 0xf149f2ca
	v_cmp_ge_i32_e32 vcc, 0, v160
	v_cndmask_b32_e32 v114, v200, v114, vcc
	v_cmp_ge_i32_e32 vcc, -1, v160
	v_cndmask_b32_e32 v115, v200, v115, vcc
	v_cmp_ge_i32_e32 vcc, -2, v160
	v_cndmask_b32_e32 v116, v200, v116, vcc
	v_cmp_ge_i32_e32 vcc, -3, v160
	v_cndmask_b32_e32 v117, v200, v117, vcc
	v_cmp_ge_i32_e32 vcc, -16, v160
	v_cndmask_b32_e32 v118, v200, v118, vcc
	v_cmp_ge_i32_e32 vcc, -17, v160
	v_cndmask_b32_e32 v119, v200, v119, vcc
	v_cmp_ge_i32_e32 vcc, -18, v160
	v_cndmask_b32_e32 v120, v200, v120, vcc
	v_cmp_ge_i32_e32 vcc, -19, v160
	v_cndmask_b32_e32 v121, v200, v121, vcc
	v_cmp_ge_i32_e32 vcc, -32, v160
	v_cndmask_b32_e32 v122, v200, v122, vcc
	v_cmp_ge_i32_e32 vcc, -33, v160
	v_cndmask_b32_e32 v123, v200, v123, vcc
	v_cmp_ge_i32_e32 vcc, -34, v160
	v_cndmask_b32_e32 v124, v200, v124, vcc
	v_cmp_ge_i32_e32 vcc, -35, v160
	v_cndmask_b32_e32 v125, v200, v125, vcc
	v_cmp_ge_i32_e32 vcc, -48, v160
	v_cndmask_b32_e32 v126, v200, v126, vcc
	v_cmp_ge_i32_e32 vcc, -49, v160
	v_cndmask_b32_e32 v127, v200, v127, vcc
	v_cmp_ge_i32_e32 vcc, -50, v160
	v_cndmask_b32_e32 v128, v200, v128, vcc
	v_cmp_ge_i32_e32 vcc, -51, v160
	v_cndmask_b32_e32 v129, v200, v129, vcc
	v_max3_f32 v179, v114, v115, v116
	v_max3_f32 v179, v179, v117, v118
	v_max3_f32 v179, v179, v119, v120
	v_max3_f32 v179, v179, v121, v122
	v_max3_f32 v179, v179, v123, v124
	v_max3_f32 v179, v179, v125, v126
	v_max3_f32 v179, v179, v127, v128
	v_max_f32_e32 v179, v179, v129
	ds_bpermute_b32 v201, v174, v179
	s_waitcnt lgkmcnt(0)
	v_max_f32_e32 v179, v179, v201
	ds_bpermute_b32 v201, v175, v179
	s_waitcnt lgkmcnt(0)
	v_max3_f32 v179, v179, v201, v176
	v_sub_f32_e32 v178, v176, v179
	v_mul_f32_e32 v178, 0x3fb8aa3b, v178
	v_exp_f32_e32 v178, v178
	v_mov_b32_e32 v176, v179
	v_mul_f32_e32 v202, 0xbfb8aa3b, v179
	v_mov_b32_e32 v203, 0x3fb8aa3b
	v_fma_f32 v114, v114, v203, v202
	v_fma_f32 v115, v115, v203, v202
	v_fma_f32 v116, v116, v203, v202
	v_fma_f32 v117, v117, v203, v202
	v_fma_f32 v118, v118, v203, v202
	v_fma_f32 v119, v119, v203, v202
	v_fma_f32 v120, v120, v203, v202
	v_fma_f32 v121, v121, v203, v202
	v_fma_f32 v122, v122, v203, v202
	v_fma_f32 v123, v123, v203, v202
	v_fma_f32 v124, v124, v203, v202
	v_fma_f32 v125, v125, v203, v202
	v_fma_f32 v126, v126, v203, v202
	v_fma_f32 v127, v127, v203, v202
	v_fma_f32 v128, v128, v203, v202
	v_fma_f32 v129, v129, v203, v202
	v_exp_f32_e32 v114, v114
	v_exp_f32_e32 v115, v115
	v_exp_f32_e32 v116, v116
	v_exp_f32_e32 v117, v117
	v_exp_f32_e32 v118, v118
	v_exp_f32_e32 v119, v119
	v_exp_f32_e32 v120, v120
	v_exp_f32_e32 v121, v121
	v_exp_f32_e32 v122, v122
	v_exp_f32_e32 v123, v123
	v_exp_f32_e32 v124, v124
	v_exp_f32_e32 v125, v125
	v_exp_f32_e32 v126, v126
	v_exp_f32_e32 v127, v127
	v_exp_f32_e32 v128, v128
	v_exp_f32_e32 v129, v129
	s_nop 0
	v_fma_f32 v177, v177, v178, v114
	v_add_f32_e32 v177, v177, v115
	v_add_f32_e32 v177, v177, v116
	v_add_f32_e32 v177, v177, v117
	v_add_f32_e32 v177, v177, v118
	v_add_f32_e32 v177, v177, v119
	v_add_f32_e32 v177, v177, v120
	v_add_f32_e32 v177, v177, v121
	v_add_f32_e32 v177, v177, v122
	v_add_f32_e32 v177, v177, v123
	v_add_f32_e32 v177, v177, v124
	v_add_f32_e32 v177, v177, v125
	v_add_f32_e32 v177, v177, v126
	v_add_f32_e32 v177, v177, v127
	v_add_f32_e32 v177, v177, v128
	v_add_f32_e32 v177, v177, v129
	v_cvt_pk_f16_f32 v130, v114, v115
	v_cvt_pk_f16_f32 v131, v116, v117
	v_cvt_pk_f16_f32 v132, v118, v119
	v_cvt_pk_f16_f32 v133, v120, v121
	v_cvt_pk_f16_f32 v134, v122, v123
	v_cvt_pk_f16_f32 v135, v124, v125
	v_cvt_pk_f16_f32 v136, v126, v127
	v_cvt_pk_f16_f32 v137, v128, v129
	v_pk_mul_f32 v[138:139], v[138:139], v[178:179] op_sel_hi:[1,0]
	v_pk_mul_f32 v[140:141], v[140:141], v[178:179] op_sel_hi:[1,0]
	v_pk_mul_f32 v[142:143], v[142:143], v[178:179] op_sel_hi:[1,0]
	v_pk_mul_f32 v[144:145], v[144:145], v[178:179] op_sel_hi:[1,0]
	v_pk_mul_f32 v[146:147], v[146:147], v[178:179] op_sel_hi:[1,0]
	v_pk_mul_f32 v[148:149], v[148:149], v[178:179] op_sel_hi:[1,0]
	v_pk_mul_f32 v[150:151], v[150:151], v[178:179] op_sel_hi:[1,0]
	v_pk_mul_f32 v[152:153], v[152:153], v[178:179] op_sel_hi:[1,0]
	s_nop 1
	v_mfma_f32_16x16x32_f16 v[138:141], v[216:219], v[130:133], v[138:141]
	v_mfma_f32_16x16x32_f16 v[142:145], v[224:227], v[130:133], v[142:145]
	v_mfma_f32_16x16x32_f16 v[146:149], v[232:235], v[130:133], v[146:149]
	v_mfma_f32_16x16x32_f16 v[150:153], v[240:243], v[130:133], v[150:153]
	v_mfma_f32_16x16x32_f16 v[138:141], v[220:223], v[134:137], v[138:141]
	v_mfma_f32_16x16x32_f16 v[142:145], v[228:231], v[134:137], v[142:145]
	v_mfma_f32_16x16x32_f16 v[146:149], v[236:239], v[134:137], v[146:149]
	v_mfma_f32_16x16x32_f16 v[150:153], v[244:247], v[134:137], v[150:153]
; DI int otid() { int t = threadIdx.x & 255; asm volatile("" : "+v"(t)); return t; }
; template <int NKB>
; DI void attn_unit(const Params& p, int l, int mode, int grp, int head, int r0, int dil, int i0, int sub_len, int W, h16* lds) {
;   unsigned char* ws = p.ws;
;   const h16* P = (const h16*)(ws + OFF_PS);
;   h16* Qi = lds; h16* Ki = lds + 64 * LDH; h16* Vt = lds + 128 * LDH; h16* Pi = lds + 192 * LDH;
;   const int tid = otid(), lane = tid & 63, w = tid >> 6, r = lane & 15, q = lane >> 4;
;   const int lrow = tid >> 2, seg = tid & 3;
;   int qcol, kcol, vcol;
;   if (mode == 0) { qcol = 1024 + grp * 256 + head * 64; kcol = 1792 + grp * 256 + head * 64; vcol = 2560 + grp * 256 + head * 64; }
;   else { qcol = 4352 + head * 64; kcol = 4864 + (head >> 2) * 64; vcol = 4992 + (head >> 2) * 64; }
;   __syncthreads();
;   {
;     const size_t pos = (size_t)r0 + (size_t)dil * (i0 + lrow);
;     const h16* g = P + pos * NSM + qcol + 16 * seg;
;     img_store_nat(Qi, lrow, seg, *(const u4v*)g, *(const u4v*)(g + 8));
;   }
;   float mrow[4], lsum[4];
;   f4v O[4];
;   float m_init = -1e30f, l_init = 0.f;
;   if (mode == 1) { m_init = p.d_sink[l * 8 + head]; l_init = 1.f; }
; #pragma unroll
;   for (int i = 0; i < 4; ++i) { mrow[i] = m_init; lsum[i] = l_init; O[i] = (f4v){0.f, 0.f, 0.f, 0.f}; }
;   u4v pk0, pk1, pv0, pv1;
;     ...
;   ATT_PREFETCH(0);
;     ...
; #pragma unroll
;   for (int rg = 0; rg < 4; ++rg) {
;     const int row = 16 * w + 4 * q + rg;
;     const size_t pos = (size_t)r0 + (size_t)dil * (i0 + row);
;     const float inv = 1.f / lsum[rg];
;     if (mode == 0) {
;       h16* ob = (h16*)(ws + OFF_OB) + ((size_t)grp * SEQ + pos) * 256 + head * 64;
; #pragma unroll
;       for (int et = 0; et < 4; ++et) ob[16 * et + r] = (h16)(O[et][rg] * inv);
;       if (r == 0) {
;         float* ml = (float*)(ws + OFF_MLB) + (((size_t)grp * SEQ + pos) * 4 + head) * 2;
;         ml[0] = mrow[rg]; ml[1] = lsum[rg];
;       }
.Lat0_kb2_end:
	s_nop 7
	s_nop 1
	ds_bpermute_b32 v201, v174, v177
	s_waitcnt lgkmcnt(0)
	v_add_f32_e32 v177, v177, v201
	ds_bpermute_b32 v201, v175, v177
	s_waitcnt lgkmcnt(0)
	v_add_f32_e32 v177, v177, v201
	v_rcp_f32_e32 v178, v177
	s_nop 0
	v_pk_mul_f32 v[138:139], v[138:139], v[178:179] op_sel_hi:[1,0]
	v_pk_mul_f32 v[140:141], v[140:141], v[178:179] op_sel_hi:[1,0]
	v_pk_mul_f32 v[142:143], v[142:143], v[178:179] op_sel_hi:[1,0]
	v_pk_mul_f32 v[144:145], v[144:145], v[178:179] op_sel_hi:[1,0]
	v_pk_mul_f32 v[146:147], v[146:147], v[178:179] op_sel_hi:[1,0]
	v_pk_mul_f32 v[148:149], v[148:149], v[178:179] op_sel_hi:[1,0]
	v_pk_mul_f32 v[150:151], v[150:151], v[178:179] op_sel_hi:[1,0]
	v_pk_mul_f32 v[152:153], v[152:153], v[178:179] op_sel_hi:[1,0]
	v_cvt_pk_f16_f32 v130, v138, v139
	v_cvt_pk_f16_f32 v131, v140, v141
	v_cvt_pk_f16_f32 v132, v142, v143
	v_cvt_pk_f16_f32 v133, v144, v145
	v_cvt_pk_f16_f32 v134, v146, v147
	v_cvt_pk_f16_f32 v135, v148, v149
	v_cvt_pk_f16_f32 v136, v150, v151
	v_cvt_pk_f16_f32 v137, v152, v153
	global_store_dwordx2 v249, v[130:131], s[48:49]
	global_store_dwordx2 v249, v[132:133], s[48:49] offset:32
	global_store_dwordx2 v249, v[134:135], s[48:49] offset:64
	global_store_dwordx2 v249, v[136:137], s[48:49] offset:96
	v_and_b32_e32 v179, 63, v182
	v_and_b32_e32 v200, 15, v179
	s_lshl_b32 s51, s58, 4
	v_add_u32_e32 v200, s51, v200
	s_lshl_b32 s51, s60, 5
	v_mul_u32_u24_e32 v200, s51, v200
	v_mov_b32_e32 v202, v176
	v_mov_b32_e32 v203, v177
	s_mov_b64 exec, 0xffff
	s_nop 1
	global_store_dwordx2 v200, v[202:203], s[16:17]
	s_nop 1
	s_mov_b64 exec, -1
.LBB0_909:
.LBB0_910:
	s_andn2_saveexec_b64 s[34:35], s[34:35]
	s_cbranch_execz .LBB0_914
	v_readfirstlane_b32 s36, v1
	v_readfirstlane_b32 s58, v182
	s_lshr_b32 s58, s58, 6
	s_sub_u32 s51, s36, 0xa8
	s_and_b32 s56, s51, 15
	s_sub_u32 s56, s56, 8
	s_and_b32 s56, s56, 15
	s_lshr_b32 s56, s56, 1
	s_lshr_b32 s57, s51, 4
	s_lshl_b32 s57, s57, 1
	s_and_b32 s59, s51, 1
	s_or_b32 s57, s57, s59
	s_lshl_b32 s56, s56, 8
	s_add_u32 s36, s56, s57
	s_and_b32 s37, s36, 7
	s_lshr_b32 s38, s36, 3
	s_lshl_b32 s38, s38, 6
	s_mov_b32 s40, 0
	s_movk_i32 s39, 0x2800
	s_mov_b32 s60, 1
	s_movk_i32 s41, 0x4000
	s_lshr_b32 s51, s37, 2
	s_lshl_b32 s51, s51, 7
	s_lshl_b32 s56, s37, 7
	s_add_u32 s53, s56, 0x2200
	s_add_u32 s54, s51, 0x2600
	s_add_u32 s55, s51, 0x2700
	v_and_b32_e32 v179, 63, v182
	v_and_b32_e32 v200, 15, v179
	v_lshrrev_b32_e32 v201, 4, v179
	v_lshlrev_b32_e32 v202, 4, v201
	v_mad_u32_u24 v2, v200, s39, v202
	v_add_u32_e32 v203, 16, v200
	v_mad_u32_u24 v3, v203, s39, v202
	v_add_u32_e32 v203, 32, v200
	v_mad_u32_u24 v4, v203, s39, v202
	v_add_u32_e32 v203, 48, v200
	v_mad_u32_u24 v5, v203, s39, v202
	s_lshl_b32 s51, s58, 4
	v_add_u32_e32 v203, s51, v200
	v_mad_u32_u24 v248, v203, s39, v202
	v_lshlrev_b32_e32 v160, 2, v201
	v_sub_u32_e32 v160, v160, v203
	v_mul_u32_u24_e32 v249, 0xa00, v203
	v_lshl_add_u32 v249, v201, 3, v249
	v_lshrrev_b32_e32 v203, 3, v179
	s_lshl_b32 s51, s58, 4
	v_add_u32_e32 v203, s51, v203
	v_and_b32_e32 v202, 7, v179
	v_lshlrev_b32_e32 v202, 4, v202
	v_mad_u32_u24 v6, v203, s39, v202
	v_add_u32_e32 v200, 8, v203
	v_mad_u32_u24 v7, v200, s39, v202
	s_movk_i32 s57, 0x90
	v_mad_u32_u24 v158, v203, s57, v183
	v_add_u32_e32 v158, v158, v202
	v_and_b32_e32 v200, 15, v179
	v_mad_u32_u24 v8, v200, s57, v183
	v_lshl_add_u32 v8, v201, 4, v8
	v_lshrrev_b32_e32 v203, 2, v179
	v_mad_u32_u24 v159, v203, s57, v183
	v_and_b32_e32 v203, 3, v179
	v_lshl_add_u32 v159, v203, 3, v159
	v_add_u32_e32 v159, 0x2400, v159
	v_xor_b32_e32 v174, 16, v179
	v_lshlrev_b32_e32 v174, 2, v174
	v_xor_b32_e32 v175, 32, v179
	v_lshlrev_b32_e32 v175, 2, v175
	s_mul_i32 s51, s60, s38
	s_add_u32 s51, s51, s40
	s_mul_i32 s56, s51, 0x2800
	s_add_u32 s56, s56, s53
	s_add_u32 s42, s0, s56
	s_addc_u32 s43, s1, 0
	global_load_dwordx4 v[10:13], v248, s[42:43]
	global_load_dwordx4 v[14:17], v248, s[42:43] offset:64
	v_readlane_b32 s48, v252, 7
	v_readlane_b32 s49, v252, 8
	s_mul_i32 s56, s38, 0xa00
	s_lshl_b32 s57, s37, 7
	s_add_u32 s56, s56, s57
	s_add_u32 s56, s56, 0x11a80600
	s_nop 2
	s_add_u32 s48, s48, s56
	s_addc_u32 s49, s49, 0
	v_readlane_b32 s18, v252, 27
	v_readlane_b32 s19, v252, 28
	s_or_b32 s56, s92, s37
	s_lshl_b32 s56, s56, 2
	s_nop 3
	s_add_u32 s18, s18, s56
	s_addc_u32 s19, s19, 0
	s_load_dword s56, s[18:19], 0x0
	v_cmp_gt_u32_e32 vcc, 16, v179
	v_cndmask_b32_e64 v177, 0, 1.0, vcc
	s_waitcnt lgkmcnt(0)
	v_mov_b32_e32 v176, s56
	v_mov_b32_e32 v138, 0
	v_mov_b32_e32 v139, 0
	v_mov_b32_e32 v140, 0
	v_mov_b32_e32 v141, 0
	v_mov_b32_e32 v142, 0
	v_mov_b32_e32 v143, 0
	v_mov_b32_e32 v144, 0
	v_mov_b32_e32 v145, 0
	v_mov_b32_e32 v146, 0
	v_mov_b32_e32 v147, 0
	v_mov_b32_e32 v148, 0
	v_mov_b32_e32 v149, 0
	v_mov_b32_e32 v150, 0
	v_mov_b32_e32 v151, 0
	v_mov_b32_e32 v152, 0
	v_mov_b32_e32 v153, 0
	s_sub_u32 s50, s38, 128
	s_cmp_ge_i32 s50, 0
	s_cselect_b32 s56, 1, 0
	s_cmp_lt_i32 s50, s41
	s_cselect_b32 s57, 1, 0
	s_and_b32 s2, s56, s57
	s_cmp_eq_u32 s2, 1
	s_cselect_b32 s50, s50, s38
	s_mul_i32 s50, s50, s60
	s_add_u32 s50, s50, s40
	s_mul_i32 s50, s50, 0x2800
	s_add_u32 s56, s50, s54
	s_add_u32 s44, s0, s56
	s_addc_u32 s45, s1, 0
	s_add_u32 s56, s50, s55
	s_add_u32 s46, s0, s56
	s_addc_u32 s47, s1, 0
	global_load_dwordx4 v[50:53], v6, s[44:45]
	global_load_dwordx4 v[54:57], v7, s[44:45]
	global_load_dwordx4 v[58:61], v6, s[46:47]
	global_load_dwordx4 v[62:65], v7, s[46:47]
	s_sub_u32 s50, s38, 64
	s_cmp_ge_i32 s50, 0
	s_cselect_b32 s56, 1, 0
	s_cmp_lt_i32 s50, s41
	s_cselect_b32 s57, 1, 0
	s_and_b32 s3, s56, s57
	s_cmp_eq_u32 s3, 1
	s_cselect_b32 s50, s50, s38
	s_mul_i32 s50, s50, s60
	s_add_u32 s50, s50, s40
	s_mul_i32 s50, s50, 0x2800
	s_add_u32 s56, s50, s54
	s_add_u32 s44, s0, s56
	s_addc_u32 s45, s1, 0
	s_add_u32 s56, s50, s55
	s_add_u32 s46, s0, s56
	s_addc_u32 s47, s1, 0
	global_load_dwordx4 v[66:69], v6, s[44:45]
	global_load_dwordx4 v[70:73], v7, s[44:45]
	global_load_dwordx4 v[74:77], v6, s[46:47]
	global_load_dwordx4 v[78:81], v7, s[46:47]
	s_waitcnt vmcnt(4)
	ds_write_b128 v158, v[50:53] offset:0
	ds_write_b128 v158, v[54:57] offset:1152
	ds_write_b128 v158, v[58:61] offset:9216
	ds_write_b128 v158, v[62:65] offset:10368
	s_waitcnt lgkmcnt(0)
	s_barrier
; DI float grp16_max(float v) { v = fmaxf(v, __shfl_xor(v, 1)); v = fmaxf(v, __shfl_xor(v, 2)); v = fmaxf(v, __shfl_xor(v, 4)); v = fmaxf(v, __shfl_xor(v, 8)); return v; }
; template <int NKB>
; DI void attn_unit(const Params& p, int l, int mode, int grp, int head, int r0, int dil, int i0, int sub_len, int W, h16* lds) {
;     ...
;   ATT_PREFETCH(0);
;   for (int kb = 0; kb < NKB; ++kb) {
;     const int j0 = i0 - W + 64 * kb;
;     const bool inr = (j0 >= 0) && (j0 < sub_len);
;     __syncthreads();
;     img_store_nat(Ki, lrow, seg, pk0, pk1);
;     img_store_T(Vt, lrow, seg, pv0, pv1);
;     __syncthreads();
;     if (kb + 1 < NKB) ATT_PREFETCH(kb + 1);
;     f4v S[4];
; #pragma unroll
;     for (int i = 0; i < 4; ++i) S[i] = (f4v){0.f, 0.f, 0.f, 0.f};
;     mm64(Qi, Ki, S, w, lane);
;     float mx[4], al[4], rsum[4];
;     bool vm[4][4];
; #pragma unroll
;     for (int rg = 0; rg < 4; ++rg) {
;       const int row = 16 * w + 4 * q + rg;
;       float m_ = -1e30f;
; #pragma unroll
;       for (int nt = 0; nt < 4; ++nt) {
;         const int key = 16 * nt + r;
;         const int delta = row - key + W - 64 * kb;
;         const bool ok = inr && (delta >= -W) && (delta <= W);
;         vm[nt][rg] = ok;
;         float s = S[nt][rg] * 0.125f;
;         S[nt][rg] = s;
;         if (ok) m_ = fmaxf(m_, s);
;       }
;       mx[rg] = grp16_max(m_);
;     }
	s_add_u32 s50, s38, 0
	s_cmp_ge_i32 s50, 0
	s_cselect_b32 s56, 1, 0
	s_cmp_lt_i32 s50, s41
	s_cselect_b32 s57, 1, 0
	s_and_b32 s4, s56, s57
	s_cmp_eq_u32 s4, 1
	s_cselect_b32 s50, s50, s38
	s_mul_i32 s50, s50, s60
	s_add_u32 s50, s50, s40
	s_mul_i32 s50, s50, 0x2800
	s_add_u32 s56, s50, s54
	s_add_u32 s44, s0, s56
	s_addc_u32 s45, s1, 0
	s_add_u32 s56, s50, s55
	s_add_u32 s46, s0, s56
	s_addc_u32 s47, s1, 0
	global_load_dwordx4 v[50:53], v6, s[44:45]
	global_load_dwordx4 v[54:57], v7, s[44:45]
	global_load_dwordx4 v[58:61], v6, s[46:47]
	global_load_dwordx4 v[62:65], v7, s[46:47]
	s_cmp_eq_u32 s2, 1
	s_cbranch_scc0 .Lat1_kb0_end
	ds_read_b128 v[18:21], v8 offset:0
	ds_read_b128 v[22:25], v8 offset:64
	ds_read_b128 v[26:29], v8 offset:2304
	ds_read_b128 v[30:33], v8 offset:2368
	ds_read_b128 v[34:37], v8 offset:4608
	ds_read_b128 v[38:41], v8 offset:4672
	ds_read_b128 v[42:45], v8 offset:6912
	ds_read_b128 v[46:49], v8 offset:6976
	ds_read_b64_tr_b16 v[216:217], v159
	ds_read_b64_tr_b16 v[218:219], v159 offset:2304
	ds_read_b64_tr_b16 v[220:221], v159 offset:4608
	ds_read_b64_tr_b16 v[222:223], v159 offset:6912
	ds_read_b64_tr_b16 v[224:225], v159 offset:32
	ds_read_b64_tr_b16 v[226:227], v159 offset:2336
	ds_read_b64_tr_b16 v[228:229], v159 offset:4640
	ds_read_b64_tr_b16 v[230:231], v159 offset:6944
	ds_read_b64_tr_b16 v[232:233], v159 offset:64
	ds_read_b64_tr_b16 v[234:235], v159 offset:2368
	ds_read_b64_tr_b16 v[236:237], v159 offset:4672
	ds_read_b64_tr_b16 v[238:239], v159 offset:6976
	ds_read_b64_tr_b16 v[240:241], v159 offset:96
	ds_read_b64_tr_b16 v[242:243], v159 offset:2400
	ds_read_b64_tr_b16 v[244:245], v159 offset:4704
	ds_read_b64_tr_b16 v[246:247], v159 offset:7008
	s_waitcnt lgkmcnt(15)
	v_mfma_f32_16x16x32_f16 v[114:117], v[18:21], v[10:13], 0
	v_mfma_f32_16x16x32_f16 v[118:121], v[26:29], v[10:13], 0
	v_mfma_f32_16x16x32_f16 v[122:125], v[34:37], v[10:13], 0
	v_mfma_f32_16x16x32_f16 v[126:129], v[42:45], v[10:13], 0
	v_mfma_f32_16x16x32_f16 v[114:117], v[22:25], v[14:17], v[114:117]
	v_mfma_f32_16x16x32_f16 v[118:121], v[30:33], v[14:17], v[118:121]
	v_mfma_f32_16x16x32_f16 v[122:125], v[38:41], v[14:17], v[122:125]
	v_mfma_f32_16x16x32_f16 v[126:129], v[46:49], v[14:17], v[126:129]
	s_nop 7
	s_nop 7
	v_mul_f32_e32 v114, 0x3e000000, v114
	v_mul_f32_e32 v115, 0x3e000000, v115
	v_mul_f32_e32 v116, 0x3e000000, v116
	v_mul_f32_e32 v117, 0x3e000000, v117
	v_mul_f32_e32 v118, 0x3e000000, v118
	v_mul_f32_e32 v119, 0x3e000000, v119
	v_mul_f32_e32 v120, 0x3e000000, v120
	v_mul_f32_e32 v121, 0x3e000000, v121
	v_mul_f32_e32 v122, 0x3e000000, v122
	v_mul_f32_e32 v123, 0x3e000000, v123
	v_mul_f32_e32 v124, 0x3e000000, v124
	v_mul_f32_e32 v125, 0x3e000000, v125
	v_mul_f32_e32 v126, 0x3e000000, v126
	v_mul_f32_e32 v127, 0x3e000000, v127
	v_mul_f32_e32 v128, 0x3e000000, v128
	v_mul_f32_e32 v129, 0x3e000000, v129
	v_mov_b32_e32 v200, 0xf149f2ca
	v_cmp_le_i32_e32 vcc, 0, v160
	v_cndmask_b32_e32 v114, v200, v114, vcc
	v_cmp_le_i32_e32 vcc, -1, v160
	v_cndmask_b32_e32 v115, v200, v115, vcc
	v_cmp_le_i32_e32 vcc, -2, v160
	v_cndmask_b32_e32 v116, v200, v116, vcc
	v_cmp_le_i32_e32 vcc, -3, v160
	v_cndmask_b32_e32 v117, v200, v117, vcc
	v_cmp_le_i32_e32 vcc, -16, v160
	v_cndmask_b32_e32 v118, v200, v118, vcc
	v_cmp_le_i32_e32 vcc, -17, v160
	v_cndmask_b32_e32 v119, v200, v119, vcc
	v_cmp_le_i32_e32 vcc, -18, v160
	v_cndmask_b32_e32 v120, v200, v120, vcc
	v_cmp_le_i32_e32 vcc, -19, v160
	v_cndmask_b32_e32 v121, v200, v121, vcc
	v_cmp_le_i32_e32 vcc, -32, v160
	v_cndmask_b32_e32 v122, v200, v122, vcc
	v_cmp_le_i32_e32 vcc, -33, v160
	v_cndmask_b32_e32 v123, v200, v123, vcc
	v_cmp_le_i32_e32 vcc, -34, v160
	v_cndmask_b32_e32 v124, v200, v124, vcc
	v_cmp_le_i32_e32 vcc, -35, v160
	v_cndmask_b32_e32 v125, v200, v125, vcc
	v_cmp_le_i32_e32 vcc, -48, v160
	v_cndmask_b32_e32 v126, v200, v126, vcc
	v_cmp_le_i32_e32 vcc, -49, v160
	v_cndmask_b32_e32 v127, v200, v127, vcc
	v_cmp_le_i32_e32 vcc, -50, v160
	v_cndmask_b32_e32 v128, v200, v128, vcc
	v_cmp_le_i32_e32 vcc, -51, v160
	v_cndmask_b32_e32 v129, v200, v129, vcc
	v_max3_f32 v179, v114, v115, v116
	v_max3_f32 v179, v179, v117, v118
	v_max3_f32 v179, v179, v119, v120
	v_max3_f32 v179, v179, v121, v122
	v_max3_f32 v179, v179, v123, v124
	v_max3_f32 v179, v179, v125, v126
	v_max3_f32 v179, v179, v127, v128
	v_max_f32_e32 v179, v179, v129
	ds_bpermute_b32 v201, v174, v179
	s_waitcnt lgkmcnt(0)
	v_max_f32_e32 v179, v179, v201
	ds_bpermute_b32 v201, v175, v179
	s_waitcnt lgkmcnt(0)
; DI float grp16_sum(float v) { v += __shfl_xor(v, 1); v += __shfl_xor(v, 2); v += __shfl_xor(v, 4); v += __shfl_xor(v, 8); return v; }
; template <int NKB>
; DI void attn_unit(const Params& p, int l, int mode, int grp, int head, int r0, int dil, int i0, int sub_len, int W, h16* lds) {
;     ...
; #pragma unroll
;     for (int rg = 0; rg < 4; ++rg) {
;       const float mn = fmaxf(mrow[rg], mx[rg]);
;       al[rg] = __expf(mrow[rg] - mn);
;       mrow[rg] = mn;
;       float rs_ = 0.f;
; #pragma unroll
;       for (int nt = 0; nt < 4; ++nt) {
;         float pv = vm[nt][rg] ? __expf(S[nt][rg] - mn) : 0.f;
;         rs_ += pv;
;         Pi[(16 * w + 4 * q + rg) * LDH + 16 * nt + r] = (h16)pv;
;       }
;       rsum[rg] = grp16_sum(rs_);
;       lsum[rg] = lsum[rg] * al[rg] + rsum[rg];
;     }
; #pragma unroll
;     for (int et = 0; et < 4; ++et)
; #pragma unroll
;       for (int rg = 0; rg < 4; ++rg) O[et][rg] *= al[rg];
;     __syncthreads();
;     mm64(Pi, Vt, O, w, lane);
	v_max3_f32 v179, v179, v201, v176
	v_sub_f32_e32 v178, v176, v179
	v_mul_f32_e32 v178, 0x3fb8aa3b, v178
	v_exp_f32_e32 v178, v178
	v_mov_b32_e32 v176, v179
	v_mul_f32_e32 v202, 0xbfb8aa3b, v179
	v_mov_b32_e32 v203, 0x3fb8aa3b
	v_fma_f32 v114, v114, v203, v202
	v_fma_f32 v115, v115, v203, v202
	v_fma_f32 v116, v116, v203, v202
	v_fma_f32 v117, v117, v203, v202
	v_fma_f32 v118, v118, v203, v202
	v_fma_f32 v119, v119, v203, v202
	v_fma_f32 v120, v120, v203, v202
	v_fma_f32 v121, v121, v203, v202
	v_fma_f32 v122, v122, v203, v202
	v_fma_f32 v123, v123, v203, v202
	v_fma_f32 v124, v124, v203, v202
	v_fma_f32 v125, v125, v203, v202
	v_fma_f32 v126, v126, v203, v202
	v_fma_f32 v127, v127, v203, v202
	v_fma_f32 v128, v128, v203, v202
	v_fma_f32 v129, v129, v203, v202
	v_exp_f32_e32 v114, v114
	v_exp_f32_e32 v115, v115
	v_exp_f32_e32 v116, v116
	v_exp_f32_e32 v117, v117
	v_exp_f32_e32 v118, v118
	v_exp_f32_e32 v119, v119
	v_exp_f32_e32 v120, v120
	v_exp_f32_e32 v121, v121
	v_exp_f32_e32 v122, v122
	v_exp_f32_e32 v123, v123
	v_exp_f32_e32 v124, v124
	v_exp_f32_e32 v125, v125
	v_exp_f32_e32 v126, v126
	v_exp_f32_e32 v127, v127
	v_exp_f32_e32 v128, v128
	v_exp_f32_e32 v129, v129
	s_nop 0
	v_fma_f32 v177, v177, v178, v114
	v_add_f32_e32 v177, v177, v115
	v_add_f32_e32 v177, v177, v116
	v_add_f32_e32 v177, v177, v117
	v_add_f32_e32 v177, v177, v118
	v_add_f32_e32 v177, v177, v119
	v_add_f32_e32 v177, v177, v120
	v_add_f32_e32 v177, v177, v121
	v_add_f32_e32 v177, v177, v122
	v_add_f32_e32 v177, v177, v123
	v_add_f32_e32 v177, v177, v124
	v_add_f32_e32 v177, v177, v125
	v_add_f32_e32 v177, v177, v126
	v_add_f32_e32 v177, v177, v127
	v_add_f32_e32 v177, v177, v128
	v_add_f32_e32 v177, v177, v129
	v_cvt_pk_f16_f32 v130, v114, v115
	v_cvt_pk_f16_f32 v131, v116, v117
	v_cvt_pk_f16_f32 v132, v118, v119
	v_cvt_pk_f16_f32 v133, v120, v121
	v_cvt_pk_f16_f32 v134, v122, v123
	v_cvt_pk_f16_f32 v135, v124, v125
	v_cvt_pk_f16_f32 v136, v126, v127
	v_cvt_pk_f16_f32 v137, v128, v129
	v_pk_mul_f32 v[138:139], v[138:139], v[178:179] op_sel_hi:[1,0]
	v_pk_mul_f32 v[140:141], v[140:141], v[178:179] op_sel_hi:[1,0]
	v_pk_mul_f32 v[142:143], v[142:143], v[178:179] op_sel_hi:[1,0]
	v_pk_mul_f32 v[144:145], v[144:145], v[178:179] op_sel_hi:[1,0]
	v_pk_mul_f32 v[146:147], v[146:147], v[178:179] op_sel_hi:[1,0]
	v_pk_mul_f32 v[148:149], v[148:149], v[178:179] op_sel_hi:[1,0]
	v_pk_mul_f32 v[150:151], v[150:151], v[178:179] op_sel_hi:[1,0]
	v_pk_mul_f32 v[152:153], v[152:153], v[178:179] op_sel_hi:[1,0]
	s_nop 1
	v_mfma_f32_16x16x32_f16 v[138:141], v[216:219], v[130:133], v[138:141]
	v_mfma_f32_16x16x32_f16 v[142:145], v[224:227], v[130:133], v[142:145]
	v_mfma_f32_16x16x32_f16 v[146:149], v[232:235], v[130:133], v[146:149]
	v_mfma_f32_16x16x32_f16 v[150:153], v[240:243], v[130:133], v[150:153]
	v_mfma_f32_16x16x32_f16 v[138:141], v[220:223], v[134:137], v[138:141]
	v_mfma_f32_16x16x32_f16 v[142:145], v[228:231], v[134:137], v[142:145]
	v_mfma_f32_16x16x32_f16 v[146:149], v[236:239], v[134:137], v[146:149]
	v_mfma_f32_16x16x32_f16 v[150:153], v[244:247], v[134:137], v[150:153]
.Lat1_kb0_end:
	s_waitcnt vmcnt(4)
	ds_write_b128 v158, v[66:69] offset:18432
	ds_write_b128 v158, v[70:73] offset:19584
	ds_write_b128 v158, v[74:77] offset:27648
	ds_write_b128 v158, v[78:81] offset:28800
	s_waitcnt lgkmcnt(0)
	s_barrier
	s_add_u32 s50, s38, 64
	s_cmp_ge_i32 s50, 0
	s_cselect_b32 s56, 1, 0
	s_cmp_lt_i32 s50, s41
	s_cselect_b32 s57, 1, 0
	s_and_b32 s5, s56, s57
	s_cmp_eq_u32 s5, 1
	s_cselect_b32 s50, s50, s38
	s_mul_i32 s50, s50, s60
	s_add_u32 s50, s50, s40
	s_mul_i32 s50, s50, 0x2800
	s_add_u32 s56, s50, s54
	s_add_u32 s44, s0, s56
	s_addc_u32 s45, s1, 0
	s_add_u32 s56, s50, s55
	s_add_u32 s46, s0, s56
	s_addc_u32 s47, s1, 0
	global_load_dwordx4 v[66:69], v6, s[44:45]
	global_load_dwordx4 v[70:73], v7, s[44:45]
	global_load_dwordx4 v[74:77], v6, s[46:47]
	global_load_dwordx4 v[78:81], v7, s[46:47]
	s_cmp_eq_u32 s3, 1
	s_cbranch_scc0 .Lat1_kb1_end
	ds_read_b128 v[18:21], v8 offset:18432
	ds_read_b128 v[22:25], v8 offset:18496
	ds_read_b128 v[26:29], v8 offset:20736
	ds_read_b128 v[30:33], v8 offset:20800
	ds_read_b128 v[34:37], v8 offset:23040
	ds_read_b128 v[38:41], v8 offset:23104
	ds_read_b128 v[42:45], v8 offset:25344
	ds_read_b128 v[46:49], v8 offset:25408
	ds_read_b64_tr_b16 v[216:217], v159 offset:18432
	ds_read_b64_tr_b16 v[218:219], v159 offset:20736
	ds_read_b64_tr_b16 v[220:221], v159 offset:23040
	ds_read_b64_tr_b16 v[222:223], v159 offset:25344
	ds_read_b64_tr_b16 v[224:225], v159 offset:18464
	ds_read_b64_tr_b16 v[226:227], v159 offset:20768
	ds_read_b64_tr_b16 v[228:229], v159 offset:23072
	ds_read_b64_tr_b16 v[230:231], v159 offset:25376
	ds_read_b64_tr_b16 v[232:233], v159 offset:18496
	ds_read_b64_tr_b16 v[234:235], v159 offset:20800
	ds_read_b64_tr_b16 v[236:237], v159 offset:23104
	ds_read_b64_tr_b16 v[238:239], v159 offset:25408
	ds_read_b64_tr_b16 v[240:241], v159 offset:18528
	ds_read_b64_tr_b16 v[242:243], v159 offset:20832
	ds_read_b64_tr_b16 v[244:245], v159 offset:23136
	ds_read_b64_tr_b16 v[246:247], v159 offset:25440
	s_waitcnt lgkmcnt(15)
; DI float grp16_sum(float v) { v += __shfl_xor(v, 1); v += __shfl_xor(v, 2); v += __shfl_xor(v, 4); v += __shfl_xor(v, 8); return v; }
; DI float grp16_max(float v) { v = fmaxf(v, __shfl_xor(v, 1)); v = fmaxf(v, __shfl_xor(v, 2)); v = fmaxf(v, __shfl_xor(v, 4)); v = fmaxf(v, __shfl_xor(v, 8)); return v; }
; template <int NKB>
; DI void attn_unit(const Params& p, int l, int mode, int grp, int head, int r0, int dil, int i0, int sub_len, int W, h16* lds) {
;     ...
; #pragma unroll
;     for (int i = 0; i < 4; ++i) S[i] = (f4v){0.f, 0.f, 0.f, 0.f};
;     mm64(Qi, Ki, S, w, lane);
;     float mx[4], al[4], rsum[4];
;     bool vm[4][4];
; #pragma unroll
;     for (int rg = 0; rg < 4; ++rg) {
;       const int row = 16 * w + 4 * q + rg;
;       float m_ = -1e30f;
; #pragma unroll
;       for (int nt = 0; nt < 4; ++nt) {
;         const int key = 16 * nt + r;
;         const int delta = row - key + W - 64 * kb;
;         const bool ok = inr && (delta >= -W) && (delta <= W);
;         vm[nt][rg] = ok;
;         float s = S[nt][rg] * 0.125f;
;         S[nt][rg] = s;
;         if (ok) m_ = fmaxf(m_, s);
;       }
;       mx[rg] = grp16_max(m_);
;     }
; #pragma unroll
;     for (int rg = 0; rg < 4; ++rg) {
;       const float mn = fmaxf(mrow[rg], mx[rg]);
;       al[rg] = __expf(mrow[rg] - mn);
;       mrow[rg] = mn;
;       float rs_ = 0.f;
; #pragma unroll
;       for (int nt = 0; nt < 4; ++nt) {
;         float pv = vm[nt][rg] ? __expf(S[nt][rg] - mn) : 0.f;
;         rs_ += pv;
;         Pi[(16 * w + 4 * q + rg) * LDH + 16 * nt + r] = (h16)pv;
;       }
;       rsum[rg] = grp16_sum(rs_);
;       lsum[rg] = lsum[rg] * al[rg] + rsum[rg];
;     }
; #pragma unroll
;     for (int et = 0; et < 4; ++et)
; #pragma unroll
;       for (int rg = 0; rg < 4; ++rg) O[et][rg] *= al[rg];
	v_mfma_f32_16x16x32_f16 v[114:117], v[18:21], v[10:13], 0
	v_mfma_f32_16x16x32_f16 v[118:121], v[26:29], v[10:13], 0
	v_mfma_f32_16x16x32_f16 v[122:125], v[34:37], v[10:13], 0
	v_mfma_f32_16x16x32_f16 v[126:129], v[42:45], v[10:13], 0
	v_mfma_f32_16x16x32_f16 v[114:117], v[22:25], v[14:17], v[114:117]
	v_mfma_f32_16x16x32_f16 v[118:121], v[30:33], v[14:17], v[118:121]
	v_mfma_f32_16x16x32_f16 v[122:125], v[38:41], v[14:17], v[122:125]
	v_mfma_f32_16x16x32_f16 v[126:129], v[46:49], v[14:17], v[126:129]
	s_nop 7
	s_nop 7
	v_mul_f32_e32 v114, 0x3e000000, v114
	v_mul_f32_e32 v115, 0x3e000000, v115
	v_mul_f32_e32 v116, 0x3e000000, v116
	v_mul_f32_e32 v117, 0x3e000000, v117
	v_mul_f32_e32 v118, 0x3e000000, v118
	v_mul_f32_e32 v119, 0x3e000000, v119
	v_mul_f32_e32 v120, 0x3e000000, v120
	v_mul_f32_e32 v121, 0x3e000000, v121
	v_mul_f32_e32 v122, 0x3e000000, v122
	v_mul_f32_e32 v123, 0x3e000000, v123
	v_mul_f32_e32 v124, 0x3e000000, v124
	v_mul_f32_e32 v125, 0x3e000000, v125
	v_mul_f32_e32 v126, 0x3e000000, v126
	v_mul_f32_e32 v127, 0x3e000000, v127
	v_mul_f32_e32 v128, 0x3e000000, v128
	v_mul_f32_e32 v129, 0x3e000000, v129
	v_max3_f32 v179, v114, v115, v116
	v_max3_f32 v179, v179, v117, v118
	v_max3_f32 v179, v179, v119, v120
	v_max3_f32 v179, v179, v121, v122
	v_max3_f32 v179, v179, v123, v124
	v_max3_f32 v179, v179, v125, v126
	v_max3_f32 v179, v179, v127, v128
	v_max_f32_e32 v179, v179, v129
	ds_bpermute_b32 v201, v174, v179
	s_waitcnt lgkmcnt(0)
	v_max_f32_e32 v179, v179, v201
	ds_bpermute_b32 v201, v175, v179
	s_waitcnt lgkmcnt(0)
	v_max3_f32 v179, v179, v201, v176
	v_sub_f32_e32 v178, v176, v179
	v_mul_f32_e32 v178, 0x3fb8aa3b, v178
	v_exp_f32_e32 v178, v178
	v_mov_b32_e32 v176, v179
	v_mul_f32_e32 v202, 0xbfb8aa3b, v179
	v_mov_b32_e32 v203, 0x3fb8aa3b
	v_fma_f32 v114, v114, v203, v202
	v_fma_f32 v115, v115, v203, v202
	v_fma_f32 v116, v116, v203, v202
	v_fma_f32 v117, v117, v203, v202
	v_fma_f32 v118, v118, v203, v202
	v_fma_f32 v119, v119, v203, v202
	v_fma_f32 v120, v120, v203, v202
	v_fma_f32 v121, v121, v203, v202
	v_fma_f32 v122, v122, v203, v202
	v_fma_f32 v123, v123, v203, v202
	v_fma_f32 v124, v124, v203, v202
	v_fma_f32 v125, v125, v203, v202
	v_fma_f32 v126, v126, v203, v202
	v_fma_f32 v127, v127, v203, v202
	v_fma_f32 v128, v128, v203, v202
	v_fma_f32 v129, v129, v203, v202
	v_exp_f32_e32 v114, v114
	v_exp_f32_e32 v115, v115
	v_exp_f32_e32 v116, v116
	v_exp_f32_e32 v117, v117
	v_exp_f32_e32 v118, v118
	v_exp_f32_e32 v119, v119
	v_exp_f32_e32 v120, v120
	v_exp_f32_e32 v121, v121
	v_exp_f32_e32 v122, v122
	v_exp_f32_e32 v123, v123
	v_exp_f32_e32 v124, v124
	v_exp_f32_e32 v125, v125
	v_exp_f32_e32 v126, v126
	v_exp_f32_e32 v127, v127
	v_exp_f32_e32 v128, v128
	v_exp_f32_e32 v129, v129
	s_nop 0
	v_fma_f32 v177, v177, v178, v114
	v_add_f32_e32 v177, v177, v115
	v_add_f32_e32 v177, v177, v116
	v_add_f32_e32 v177, v177, v117
	v_add_f32_e32 v177, v177, v118
	v_add_f32_e32 v177, v177, v119
	v_add_f32_e32 v177, v177, v120
	v_add_f32_e32 v177, v177, v121
	v_add_f32_e32 v177, v177, v122
	v_add_f32_e32 v177, v177, v123
	v_add_f32_e32 v177, v177, v124
	v_add_f32_e32 v177, v177, v125
	v_add_f32_e32 v177, v177, v126
	v_add_f32_e32 v177, v177, v127
	v_add_f32_e32 v177, v177, v128
	v_add_f32_e32 v177, v177, v129
	v_cvt_pk_f16_f32 v130, v114, v115
	v_cvt_pk_f16_f32 v131, v116, v117
	v_cvt_pk_f16_f32 v132, v118, v119
	v_cvt_pk_f16_f32 v133, v120, v121
	v_cvt_pk_f16_f32 v134, v122, v123
	v_cvt_pk_f16_f32 v135, v124, v125
	v_cvt_pk_f16_f32 v136, v126, v127
	v_cvt_pk_f16_f32 v137, v128, v129
	v_pk_mul_f32 v[138:139], v[138:139], v[178:179] op_sel_hi:[1,0]
	v_pk_mul_f32 v[140:141], v[140:141], v[178:179] op_sel_hi:[1,0]
	v_pk_mul_f32 v[142:143], v[142:143], v[178:179] op_sel_hi:[1,0]
	v_pk_mul_f32 v[144:145], v[144:145], v[178:179] op_sel_hi:[1,0]
	v_pk_mul_f32 v[146:147], v[146:147], v[178:179] op_sel_hi:[1,0]
	v_pk_mul_f32 v[148:149], v[148:149], v[178:179] op_sel_hi:[1,0]
	v_pk_mul_f32 v[150:151], v[150:151], v[178:179] op_sel_hi:[1,0]
	v_pk_mul_f32 v[152:153], v[152:153], v[178:179] op_sel_hi:[1,0]
	s_nop 1
	v_mfma_f32_16x16x32_f16 v[138:141], v[216:219], v[130:133], v[138:141]
	v_mfma_f32_16x16x32_f16 v[142:145], v[224:227], v[130:133], v[142:145]
	v_mfma_f32_16x16x32_f16 v[146:149], v[232:235], v[130:133], v[146:149]
	v_mfma_f32_16x16x32_f16 v[150:153], v[240:243], v[130:133], v[150:153]
	v_mfma_f32_16x16x32_f16 v[138:141], v[220:223], v[134:137], v[138:141]
	v_mfma_f32_16x16x32_f16 v[142:145], v[228:231], v[134:137], v[142:145]
	v_mfma_f32_16x16x32_f16 v[146:149], v[236:239], v[134:137], v[146:149]
	v_mfma_f32_16x16x32_f16 v[150:153], v[244:247], v[134:137], v[150:153]
; DI float grp16_sum(float v) { v += __shfl_xor(v, 1); v += __shfl_xor(v, 2); v += __shfl_xor(v, 4); v += __shfl_xor(v, 8); return v; }
; DI float grp16_max(float v) { v = fmaxf(v, __shfl_xor(v, 1)); v = fmaxf(v, __shfl_xor(v, 2)); v = fmaxf(v, __shfl_xor(v, 4)); v = fmaxf(v, __shfl_xor(v, 8)); return v; }
; template <int NKB>
; DI void attn_unit(const Params& p, int l, int mode, int grp, int head, int r0, int dil, int i0, int sub_len, int W, h16* lds) {
;     ...
;   for (int kb = 0; kb < NKB; ++kb) {
;     const int j0 = i0 - W + 64 * kb;
;     const bool inr = (j0 >= 0) && (j0 < sub_len);
;     __syncthreads();
;     img_store_nat(Ki, lrow, seg, pk0, pk1);
;     img_store_T(Vt, lrow, seg, pv0, pv1);
;     __syncthreads();
;     if (kb + 1 < NKB) ATT_PREFETCH(kb + 1);
;     f4v S[4];
; #pragma unroll
;     for (int i = 0; i < 4; ++i) S[i] = (f4v){0.f, 0.f, 0.f, 0.f};
;     mm64(Qi, Ki, S, w, lane);
;     float mx[4], al[4], rsum[4];
;     bool vm[4][4];
; #pragma unroll
;     for (int rg = 0; rg < 4; ++rg) {
;       const int row = 16 * w + 4 * q + rg;
;       float m_ = -1e30f;
; #pragma unroll
;       for (int nt = 0; nt < 4; ++nt) {
;         const int key = 16 * nt + r;
;         const int delta = row - key + W - 64 * kb;
;         const bool ok = inr && (delta >= -W) && (delta <= W);
;         vm[nt][rg] = ok;
;         float s = S[nt][rg] * 0.125f;
;         S[nt][rg] = s;
;         if (ok) m_ = fmaxf(m_, s);
;       }
;       mx[rg] = grp16_max(m_);
;     }
; #pragma unroll
;     for (int rg = 0; rg < 4; ++rg) {
;       const float mn = fmaxf(mrow[rg], mx[rg]);
;       al[rg] = __expf(mrow[rg] - mn);
;       mrow[rg] = mn;
;       float rs_ = 0.f;
; #pragma unroll
;       for (int nt = 0; nt < 4; ++nt) {
;         float pv = vm[nt][rg] ? __expf(S[nt][rg] - mn) : 0.f;
;         rs_ += pv;
;         Pi[(16 * w + 4 * q + rg) * LDH + 16 * nt + r] = (h16)pv;
;       }
;       rsum[rg] = grp16_sum(rs_);
;       lsum[rg] = lsum[rg] * al[rg] + rsum[rg];
;     }
; #pragma unroll
;     for (int et = 0; et < 4; ++et)
; #pragma unroll
;       for (int rg = 0; rg < 4; ++rg) O[et][rg] *= al[rg];
.Lat1_kb1_end:
	s_waitcnt vmcnt(4)
	ds_write_b128 v158, v[50:53] offset:36864
	ds_write_b128 v158, v[54:57] offset:38016
	ds_write_b128 v158, v[58:61] offset:46080
	ds_write_b128 v158, v[62:65] offset:47232
	s_waitcnt lgkmcnt(0)
	s_barrier
	s_add_u32 s50, s38, 128
	s_cmp_ge_i32 s50, 0
	s_cselect_b32 s56, 1, 0
	s_cmp_lt_i32 s50, s41
	s_cselect_b32 s57, 1, 0
	s_and_b32 s6, s56, s57
	s_cmp_eq_u32 s6, 1
	s_cselect_b32 s50, s50, s38
	s_mul_i32 s50, s50, s60
	s_add_u32 s50, s50, s40
	s_mul_i32 s50, s50, 0x2800
	s_add_u32 s56, s50, s54
	s_add_u32 s44, s0, s56
	s_addc_u32 s45, s1, 0
	s_add_u32 s56, s50, s55
	s_add_u32 s46, s0, s56
	s_addc_u32 s47, s1, 0
	global_load_dwordx4 v[50:53], v6, s[44:45]
	global_load_dwordx4 v[54:57], v7, s[44:45]
	global_load_dwordx4 v[58:61], v6, s[46:47]
	global_load_dwordx4 v[62:65], v7, s[46:47]
	s_cmp_eq_u32 s4, 1
	s_cbranch_scc0 .Lat1_kb2_end
	ds_read_b128 v[18:21], v8 offset:36864
	ds_read_b128 v[22:25], v8 offset:36928
	ds_read_b128 v[26:29], v8 offset:39168
	ds_read_b128 v[30:33], v8 offset:39232
	ds_read_b128 v[34:37], v8 offset:41472
	ds_read_b128 v[38:41], v8 offset:41536
	ds_read_b128 v[42:45], v8 offset:43776
	ds_read_b128 v[46:49], v8 offset:43840
	ds_read_b64_tr_b16 v[216:217], v159 offset:36864
	ds_read_b64_tr_b16 v[218:219], v159 offset:39168
	ds_read_b64_tr_b16 v[220:221], v159 offset:41472
	ds_read_b64_tr_b16 v[222:223], v159 offset:43776
	ds_read_b64_tr_b16 v[224:225], v159 offset:36896
	ds_read_b64_tr_b16 v[226:227], v159 offset:39200
	ds_read_b64_tr_b16 v[228:229], v159 offset:41504
	ds_read_b64_tr_b16 v[230:231], v159 offset:43808
	ds_read_b64_tr_b16 v[232:233], v159 offset:36928
	ds_read_b64_tr_b16 v[234:235], v159 offset:39232
	ds_read_b64_tr_b16 v[236:237], v159 offset:41536
	ds_read_b64_tr_b16 v[238:239], v159 offset:43840
	ds_read_b64_tr_b16 v[240:241], v159 offset:36960
	ds_read_b64_tr_b16 v[242:243], v159 offset:39264
	ds_read_b64_tr_b16 v[244:245], v159 offset:41568
	ds_read_b64_tr_b16 v[246:247], v159 offset:43872
	s_waitcnt lgkmcnt(15)
	v_mfma_f32_16x16x32_f16 v[114:117], v[18:21], v[10:13], 0
	v_mfma_f32_16x16x32_f16 v[118:121], v[26:29], v[10:13], 0
	v_mfma_f32_16x16x32_f16 v[122:125], v[34:37], v[10:13], 0
	v_mfma_f32_16x16x32_f16 v[126:129], v[42:45], v[10:13], 0
	v_mfma_f32_16x16x32_f16 v[114:117], v[22:25], v[14:17], v[114:117]
	v_mfma_f32_16x16x32_f16 v[118:121], v[30:33], v[14:17], v[118:121]
	v_mfma_f32_16x16x32_f16 v[122:125], v[38:41], v[14:17], v[122:125]
	v_mfma_f32_16x16x32_f16 v[126:129], v[46:49], v[14:17], v[126:129]
	s_nop 7
	s_nop 7
	v_mul_f32_e32 v114, 0x3e000000, v114
	v_mul_f32_e32 v115, 0x3e000000, v115
	v_mul_f32_e32 v116, 0x3e000000, v116
	v_mul_f32_e32 v117, 0x3e000000, v117
	v_mul_f32_e32 v118, 0x3e000000, v118
	v_mul_f32_e32 v119, 0x3e000000, v119
	v_mul_f32_e32 v120, 0x3e000000, v120
	v_mul_f32_e32 v121, 0x3e000000, v121
	v_mul_f32_e32 v122, 0x3e000000, v122
	v_mul_f32_e32 v123, 0x3e000000, v123
	v_mul_f32_e32 v124, 0x3e000000, v124
	v_mul_f32_e32 v125, 0x3e000000, v125
	v_mul_f32_e32 v126, 0x3e000000, v126
	v_mul_f32_e32 v127, 0x3e000000, v127
	v_mul_f32_e32 v128, 0x3e000000, v128
	v_mul_f32_e32 v129, 0x3e000000, v129
	v_max3_f32 v179, v114, v115, v116
	v_max3_f32 v179, v179, v117, v118
	v_max3_f32 v179, v179, v119, v120
	v_max3_f32 v179, v179, v121, v122
	v_max3_f32 v179, v179, v123, v124
	v_max3_f32 v179, v179, v125, v126
	v_max3_f32 v179, v179, v127, v128
	v_max_f32_e32 v179, v179, v129
	ds_bpermute_b32 v201, v174, v179
	s_waitcnt lgkmcnt(0)
	v_max_f32_e32 v179, v179, v201
	ds_bpermute_b32 v201, v175, v179
	s_waitcnt lgkmcnt(0)
	v_max3_f32 v179, v179, v201, v176
	v_sub_f32_e32 v178, v176, v179
	v_mul_f32_e32 v178, 0x3fb8aa3b, v178
	v_exp_f32_e32 v178, v178
	v_mov_b32_e32 v176, v179
	v_mul_f32_e32 v202, 0xbfb8aa3b, v179
	v_mov_b32_e32 v203, 0x3fb8aa3b
	v_fma_f32 v114, v114, v203, v202
	v_fma_f32 v115, v115, v203, v202
	v_fma_f32 v116, v116, v203, v202
	v_fma_f32 v117, v117, v203, v202
	v_fma_f32 v118, v118, v203, v202
	v_fma_f32 v119, v119, v203, v202
	v_fma_f32 v120, v120, v203, v202
	v_fma_f32 v121, v121, v203, v202
	v_fma_f32 v122, v122, v203, v202
	v_fma_f32 v123, v123, v203, v202
	v_fma_f32 v124, v124, v203, v202
	v_fma_f32 v125, v125, v203, v202
	v_fma_f32 v126, v126, v203, v202
	v_fma_f32 v127, v127, v203, v202
	v_fma_f32 v128, v128, v203, v202
	v_fma_f32 v129, v129, v203, v202
	v_exp_f32_e32 v114, v114
	v_exp_f32_e32 v115, v115
	v_exp_f32_e32 v116, v116
	v_exp_f32_e32 v117, v117
	v_exp_f32_e32 v118, v118
	v_exp_f32_e32 v119, v119
	v_exp_f32_e32 v120, v120
	v_exp_f32_e32 v121, v121
	v_exp_f32_e32 v122, v122
	v_exp_f32_e32 v123, v123
	v_exp_f32_e32 v124, v124
	v_exp_f32_e32 v125, v125
	v_exp_f32_e32 v126, v126
	v_exp_f32_e32 v127, v127
	v_exp_f32_e32 v128, v128
	v_exp_f32_e32 v129, v129
	s_nop 0
	v_fma_f32 v177, v177, v178, v114
	v_add_f32_e32 v177, v177, v115
	v_add_f32_e32 v177, v177, v116
	v_add_f32_e32 v177, v177, v117
	v_add_f32_e32 v177, v177, v118
	v_add_f32_e32 v177, v177, v119
	v_add_f32_e32 v177, v177, v120
	v_add_f32_e32 v177, v177, v121
	v_add_f32_e32 v177, v177, v122
	v_add_f32_e32 v177, v177, v123
	v_add_f32_e32 v177, v177, v124
	v_add_f32_e32 v177, v177, v125
	v_add_f32_e32 v177, v177, v126
	v_add_f32_e32 v177, v177, v127
	v_add_f32_e32 v177, v177, v128
	v_add_f32_e32 v177, v177, v129
	v_cvt_pk_f16_f32 v130, v114, v115
	v_cvt_pk_f16_f32 v131, v116, v117
	v_cvt_pk_f16_f32 v132, v118, v119
	v_cvt_pk_f16_f32 v133, v120, v121
	v_cvt_pk_f16_f32 v134, v122, v123
	v_cvt_pk_f16_f32 v135, v124, v125
	v_cvt_pk_f16_f32 v136, v126, v127
	v_cvt_pk_f16_f32 v137, v128, v129
	v_pk_mul_f32 v[138:139], v[138:139], v[178:179] op_sel_hi:[1,0]
	v_pk_mul_f32 v[140:141], v[140:141], v[178:179] op_sel_hi:[1,0]
	v_pk_mul_f32 v[142:143], v[142:143], v[178:179] op_sel_hi:[1,0]
	v_pk_mul_f32 v[144:145], v[144:145], v[178:179] op_sel_hi:[1,0]
	v_pk_mul_f32 v[146:147], v[146:147], v[178:179] op_sel_hi:[1,0]
	v_pk_mul_f32 v[148:149], v[148:149], v[178:179] op_sel_hi:[1,0]
	v_pk_mul_f32 v[150:151], v[150:151], v[178:179] op_sel_hi:[1,0]
	v_pk_mul_f32 v[152:153], v[152:153], v[178:179] op_sel_hi:[1,0]
	s_nop 1
	v_mfma_f32_16x16x32_f16 v[138:141], v[216:219], v[130:133], v[138:141]
	v_mfma_f32_16x16x32_f16 v[142:145], v[224:227], v[130:133], v[142:145]
	v_mfma_f32_16x16x32_f16 v[146:149], v[232:235], v[130:133], v[146:149]
	v_mfma_f32_16x16x32_f16 v[150:153], v[240:243], v[130:133], v[150:153]
	v_mfma_f32_16x16x32_f16 v[138:141], v[220:223], v[134:137], v[138:141]
	v_mfma_f32_16x16x32_f16 v[142:145], v[228:231], v[134:137], v[142:145]
	v_mfma_f32_16x16x32_f16 v[146:149], v[236:239], v[134:137], v[146:149]
	v_mfma_f32_16x16x32_f16 v[150:153], v[244:247], v[134:137], v[150:153]
; DI float grp16_sum(float v) { v += __shfl_xor(v, 1); v += __shfl_xor(v, 2); v += __shfl_xor(v, 4); v += __shfl_xor(v, 8); return v; }
; DI float grp16_max(float v) { v = fmaxf(v, __shfl_xor(v, 1)); v = fmaxf(v, __shfl_xor(v, 2)); v = fmaxf(v, __shfl_xor(v, 4)); v = fmaxf(v, __shfl_xor(v, 8)); return v; }
; template <int NKB>
; DI void attn_unit(const Params& p, int l, int mode, int grp, int head, int r0, int dil, int i0, int sub_len, int W, h16* lds) {
;     ...
;   for (int kb = 0; kb < NKB; ++kb) {
;     const int j0 = i0 - W + 64 * kb;
;     const bool inr = (j0 >= 0) && (j0 < sub_len);
;     __syncthreads();
;     img_store_nat(Ki, lrow, seg, pk0, pk1);
;     img_store_T(Vt, lrow, seg, pv0, pv1);
;     __syncthreads();
;     if (kb + 1 < NKB) ATT_PREFETCH(kb + 1);
;     f4v S[4];
; #pragma unroll
;     for (int i = 0; i < 4; ++i) S[i] = (f4v){0.f, 0.f, 0.f, 0.f};
;     mm64(Qi, Ki, S, w, lane);
;     float mx[4], al[4], rsum[4];
;     bool vm[4][4];
; #pragma unroll
;     for (int rg = 0; rg < 4; ++rg) {
;       const int row = 16 * w + 4 * q + rg;
;       float m_ = -1e30f;
; #pragma unroll
;       for (int nt = 0; nt < 4; ++nt) {
;         const int key = 16 * nt + r;
;         const int delta = row - key + W - 64 * kb;
;         const bool ok = inr && (delta >= -W) && (delta <= W);
;         vm[nt][rg] = ok;
;         float s = S[nt][rg] * 0.125f;
;         S[nt][rg] = s;
;         if (ok) m_ = fmaxf(m_, s);
;       }
;       mx[rg] = grp16_max(m_);
;     }
; #pragma unroll
;     for (int rg = 0; rg < 4; ++rg) {
;       const float mn = fmaxf(mrow[rg], mx[rg]);
;       al[rg] = __expf(mrow[rg] - mn);
;       mrow[rg] = mn;
;       float rs_ = 0.f;
; #pragma unroll
;       for (int nt = 0; nt < 4; ++nt) {
;         float pv = vm[nt][rg] ? __expf(S[nt][rg] - mn) : 0.f;
;         rs_ += pv;
;         Pi[(16 * w + 4 * q + rg) * LDH + 16 * nt + r] = (h16)pv;
;       }
;       rsum[rg] = grp16_sum(rs_);
;       lsum[rg] = lsum[rg] * al[rg] + rsum[rg];
;     }
; #pragma unroll
;     for (int et = 0; et < 4; ++et)
; #pragma unroll
;       for (int rg = 0; rg < 4; ++rg) O[et][rg] *= al[rg];
.Lat1_kb2_end:
	s_waitcnt vmcnt(4)
	ds_write_b128 v158, v[66:69] offset:0
	ds_write_b128 v158, v[70:73] offset:1152
	ds_write_b128 v158, v[74:77] offset:9216
	ds_write_b128 v158, v[78:81] offset:10368
	s_waitcnt lgkmcnt(0)
	s_barrier
	s_cmp_eq_u32 s5, 1
	s_cbranch_scc0 .Lat1_kb3_end
	ds_read_b128 v[18:21], v8 offset:0
	ds_read_b128 v[22:25], v8 offset:64
	ds_read_b128 v[26:29], v8 offset:2304
	ds_read_b128 v[30:33], v8 offset:2368
	ds_read_b128 v[34:37], v8 offset:4608
	ds_read_b128 v[38:41], v8 offset:4672
	ds_read_b128 v[42:45], v8 offset:6912
	ds_read_b128 v[46:49], v8 offset:6976
	ds_read_b64_tr_b16 v[216:217], v159
	ds_read_b64_tr_b16 v[218:219], v159 offset:2304
	ds_read_b64_tr_b16 v[220:221], v159 offset:4608
	ds_read_b64_tr_b16 v[222:223], v159 offset:6912
	ds_read_b64_tr_b16 v[224:225], v159 offset:32
	ds_read_b64_tr_b16 v[226:227], v159 offset:2336
	ds_read_b64_tr_b16 v[228:229], v159 offset:4640
	ds_read_b64_tr_b16 v[230:231], v159 offset:6944
	ds_read_b64_tr_b16 v[232:233], v159 offset:64
	ds_read_b64_tr_b16 v[234:235], v159 offset:2368
	ds_read_b64_tr_b16 v[236:237], v159 offset:4672
	ds_read_b64_tr_b16 v[238:239], v159 offset:6976
	ds_read_b64_tr_b16 v[240:241], v159 offset:96
	ds_read_b64_tr_b16 v[242:243], v159 offset:2400
	ds_read_b64_tr_b16 v[244:245], v159 offset:4704
	ds_read_b64_tr_b16 v[246:247], v159 offset:7008
	s_waitcnt lgkmcnt(15)
	v_mfma_f32_16x16x32_f16 v[114:117], v[18:21], v[10:13], 0
	v_mfma_f32_16x16x32_f16 v[118:121], v[26:29], v[10:13], 0
	v_mfma_f32_16x16x32_f16 v[122:125], v[34:37], v[10:13], 0
	v_mfma_f32_16x16x32_f16 v[126:129], v[42:45], v[10:13], 0
	v_mfma_f32_16x16x32_f16 v[114:117], v[22:25], v[14:17], v[114:117]
	v_mfma_f32_16x16x32_f16 v[118:121], v[30:33], v[14:17], v[118:121]
	v_mfma_f32_16x16x32_f16 v[122:125], v[38:41], v[14:17], v[122:125]
	v_mfma_f32_16x16x32_f16 v[126:129], v[46:49], v[14:17], v[126:129]
	s_nop 7
	s_nop 7
	v_mul_f32_e32 v114, 0x3e000000, v114
	v_mul_f32_e32 v115, 0x3e000000, v115
	v_mul_f32_e32 v116, 0x3e000000, v116
	v_mul_f32_e32 v117, 0x3e000000, v117
	v_mul_f32_e32 v118, 0x3e000000, v118
	v_mul_f32_e32 v119, 0x3e000000, v119
	v_mul_f32_e32 v120, 0x3e000000, v120
	v_mul_f32_e32 v121, 0x3e000000, v121
	v_mul_f32_e32 v122, 0x3e000000, v122
	v_mul_f32_e32 v123, 0x3e000000, v123
	v_mul_f32_e32 v124, 0x3e000000, v124
	v_mul_f32_e32 v125, 0x3e000000, v125
	v_mul_f32_e32 v126, 0x3e000000, v126
	v_mul_f32_e32 v127, 0x3e000000, v127
	v_mul_f32_e32 v128, 0x3e000000, v128
	v_mul_f32_e32 v129, 0x3e000000, v129
	v_max3_f32 v179, v114, v115, v116
	v_max3_f32 v179, v179, v117, v118
	v_max3_f32 v179, v179, v119, v120
	v_max3_f32 v179, v179, v121, v122
	v_max3_f32 v179, v179, v123, v124
	v_max3_f32 v179, v179, v125, v126
	v_max3_f32 v179, v179, v127, v128
	v_max_f32_e32 v179, v179, v129
	ds_bpermute_b32 v201, v174, v179
	s_waitcnt lgkmcnt(0)
	v_max_f32_e32 v179, v179, v201
	ds_bpermute_b32 v201, v175, v179
	s_waitcnt lgkmcnt(0)
	v_max3_f32 v179, v179, v201, v176
	v_sub_f32_e32 v178, v176, v179
	v_mul_f32_e32 v178, 0x3fb8aa3b, v178
	v_exp_f32_e32 v178, v178
	v_mov_b32_e32 v176, v179
	v_mul_f32_e32 v202, 0xbfb8aa3b, v179
	v_mov_b32_e32 v203, 0x3fb8aa3b
	v_fma_f32 v114, v114, v203, v202
	v_fma_f32 v115, v115, v203, v202
	v_fma_f32 v116, v116, v203, v202
	v_fma_f32 v117, v117, v203, v202
	v_fma_f32 v118, v118, v203, v202
	v_fma_f32 v119, v119, v203, v202
	v_fma_f32 v120, v120, v203, v202
	v_fma_f32 v121, v121, v203, v202
	v_fma_f32 v122, v122, v203, v202
	v_fma_f32 v123, v123, v203, v202
	v_fma_f32 v124, v124, v203, v202
	v_fma_f32 v125, v125, v203, v202
	v_fma_f32 v126, v126, v203, v202
	v_fma_f32 v127, v127, v203, v202
	v_fma_f32 v128, v128, v203, v202
	v_fma_f32 v129, v129, v203, v202
	v_exp_f32_e32 v114, v114
	v_exp_f32_e32 v115, v115
	v_exp_f32_e32 v116, v116
	v_exp_f32_e32 v117, v117
	v_exp_f32_e32 v118, v118
	v_exp_f32_e32 v119, v119
	v_exp_f32_e32 v120, v120
	v_exp_f32_e32 v121, v121
	v_exp_f32_e32 v122, v122
	v_exp_f32_e32 v123, v123
	v_exp_f32_e32 v124, v124
	v_exp_f32_e32 v125, v125
	v_exp_f32_e32 v126, v126
	v_exp_f32_e32 v127, v127
	v_exp_f32_e32 v128, v128
	v_exp_f32_e32 v129, v129
	s_nop 0
	v_fma_f32 v177, v177, v178, v114
	v_add_f32_e32 v177, v177, v115
	v_add_f32_e32 v177, v177, v116
	v_add_f32_e32 v177, v177, v117
	v_add_f32_e32 v177, v177, v118
	v_add_f32_e32 v177, v177, v119
	v_add_f32_e32 v177, v177, v120
	v_add_f32_e32 v177, v177, v121
	v_add_f32_e32 v177, v177, v122
	v_add_f32_e32 v177, v177, v123
	v_add_f32_e32 v177, v177, v124
	v_add_f32_e32 v177, v177, v125
	v_add_f32_e32 v177, v177, v126
	v_add_f32_e32 v177, v177, v127
	v_add_f32_e32 v177, v177, v128
	v_add_f32_e32 v177, v177, v129
	v_cvt_pk_f16_f32 v130, v114, v115
	v_cvt_pk_f16_f32 v131, v116, v117
	v_cvt_pk_f16_f32 v132, v118, v119
	v_cvt_pk_f16_f32 v133, v120, v121
	v_cvt_pk_f16_f32 v134, v122, v123
	v_cvt_pk_f16_f32 v135, v124, v125
	v_cvt_pk_f16_f32 v136, v126, v127
	v_cvt_pk_f16_f32 v137, v128, v129
	v_pk_mul_f32 v[138:139], v[138:139], v[178:179] op_sel_hi:[1,0]
	v_pk_mul_f32 v[140:141], v[140:141], v[178:179] op_sel_hi:[1,0]
	v_pk_mul_f32 v[142:143], v[142:143], v[178:179] op_sel_hi:[1,0]
	v_pk_mul_f32 v[144:145], v[144:145], v[178:179] op_sel_hi:[1,0]
	v_pk_mul_f32 v[146:147], v[146:147], v[178:179] op_sel_hi:[1,0]
	v_pk_mul_f32 v[148:149], v[148:149], v[178:179] op_sel_hi:[1,0]
	v_pk_mul_f32 v[150:151], v[150:151], v[178:179] op_sel_hi:[1,0]
	v_pk_mul_f32 v[152:153], v[152:153], v[178:179] op_sel_hi:[1,0]
	s_nop 1
	v_mfma_f32_16x16x32_f16 v[138:141], v[216:219], v[130:133], v[138:141]
	v_mfma_f32_16x16x32_f16 v[142:145], v[224:227], v[130:133], v[142:145]
	v_mfma_f32_16x16x32_f16 v[146:149], v[232:235], v[130:133], v[146:149]
	v_mfma_f32_16x16x32_f16 v[150:153], v[240:243], v[130:133], v[150:153]
	v_mfma_f32_16x16x32_f16 v[138:141], v[220:223], v[134:137], v[138:141]
	v_mfma_f32_16x16x32_f16 v[142:145], v[228:231], v[134:137], v[142:145]
	v_mfma_f32_16x16x32_f16 v[146:149], v[236:239], v[134:137], v[146:149]
	v_mfma_f32_16x16x32_f16 v[150:153], v[244:247], v[134:137], v[150:153]
; DI float grp16_max(float v) { v = fmaxf(v, __shfl_xor(v, 1)); v = fmaxf(v, __shfl_xor(v, 2)); v = fmaxf(v, __shfl_xor(v, 4)); v = fmaxf(v, __shfl_xor(v, 8)); return v; }
; template <int NKB>
; DI void attn_unit(const Params& p, int l, int mode, int grp, int head, int r0, int dil, int i0, int sub_len, int W, h16* lds) {
;     ...
;   for (int kb = 0; kb < NKB; ++kb) {
;     const int j0 = i0 - W + 64 * kb;
;     const bool inr = (j0 >= 0) && (j0 < sub_len);
;     __syncthreads();
;     img_store_nat(Ki, lrow, seg, pk0, pk1);
;     img_store_T(Vt, lrow, seg, pv0, pv1);
;     __syncthreads();
;     if (kb + 1 < NKB) ATT_PREFETCH(kb + 1);
;     f4v S[4];
; #pragma unroll
;     for (int i = 0; i < 4; ++i) S[i] = (f4v){0.f, 0.f, 0.f, 0.f};
;     mm64(Qi, Ki, S, w, lane);
;     float mx[4], al[4], rsum[4];
;     bool vm[4][4];
; #pragma unroll
;     for (int rg = 0; rg < 4; ++rg) {
;       const int row = 16 * w + 4 * q + rg;
;       float m_ = -1e30f;
; #pragma unroll
;       for (int nt = 0; nt < 4; ++nt) {
;         const int key = 16 * nt + r;
;         const int delta = row - key + W - 64 * kb;
;         const bool ok = inr && (delta >= -W) && (delta <= W);
;         vm[nt][rg] = ok;
;         float s = S[nt][rg] * 0.125f;
;         S[nt][rg] = s;
;         if (ok) m_ = fmaxf(m_, s);
;       }
;       mx[rg] = grp16_max(m_);
;     }
.Lat1_kb3_end:
	s_waitcnt vmcnt(0)
	ds_write_b128 v158, v[50:53] offset:18432
	ds_write_b128 v158, v[54:57] offset:19584
	ds_write_b128 v158, v[58:61] offset:27648
	ds_write_b128 v158, v[62:65] offset:28800
	s_waitcnt lgkmcnt(0)
	s_barrier
	s_cmp_eq_u32 s6, 1
	s_cbranch_scc0 .Lat1_kb4_end
	ds_read_b128 v[18:21], v8 offset:18432
	ds_read_b128 v[22:25], v8 offset:18496
	ds_read_b128 v[26:29], v8 offset:20736
	ds_read_b128 v[30:33], v8 offset:20800
	ds_read_b128 v[34:37], v8 offset:23040
	ds_read_b128 v[38:41], v8 offset:23104
	ds_read_b128 v[42:45], v8 offset:25344
	ds_read_b128 v[46:49], v8 offset:25408
	ds_read_b64_tr_b16 v[216:217], v159 offset:18432
	ds_read_b64_tr_b16 v[218:219], v159 offset:20736
	ds_read_b64_tr_b16 v[220:221], v159 offset:23040
	ds_read_b64_tr_b16 v[222:223], v159 offset:25344
	ds_read_b64_tr_b16 v[224:225], v159 offset:18464
	ds_read_b64_tr_b16 v[226:227], v159 offset:20768
	ds_read_b64_tr_b16 v[228:229], v159 offset:23072
	ds_read_b64_tr_b16 v[230:231], v159 offset:25376
	ds_read_b64_tr_b16 v[232:233], v159 offset:18496
	ds_read_b64_tr_b16 v[234:235], v159 offset:20800
	ds_read_b64_tr_b16 v[236:237], v159 offset:23104
	ds_read_b64_tr_b16 v[238:239], v159 offset:25408
	ds_read_b64_tr_b16 v[240:241], v159 offset:18528
	ds_read_b64_tr_b16 v[242:243], v159 offset:20832
	ds_read_b64_tr_b16 v[244:245], v159 offset:23136
	ds_read_b64_tr_b16 v[246:247], v159 offset:25440
	s_waitcnt lgkmcnt(15)
	v_mfma_f32_16x16x32_f16 v[114:117], v[18:21], v[10:13], 0
	v_mfma_f32_16x16x32_f16 v[118:121], v[26:29], v[10:13], 0
	v_mfma_f32_16x16x32_f16 v[122:125], v[34:37], v[10:13], 0
	v_mfma_f32_16x16x32_f16 v[126:129], v[42:45], v[10:13], 0
	v_mfma_f32_16x16x32_f16 v[114:117], v[22:25], v[14:17], v[114:117]
	v_mfma_f32_16x16x32_f16 v[118:121], v[30:33], v[14:17], v[118:121]
	v_mfma_f32_16x16x32_f16 v[122:125], v[38:41], v[14:17], v[122:125]
	v_mfma_f32_16x16x32_f16 v[126:129], v[46:49], v[14:17], v[126:129]
	s_nop 7
	s_nop 7
	v_mul_f32_e32 v114, 0x3e000000, v114
	v_mul_f32_e32 v115, 0x3e000000, v115
	v_mul_f32_e32 v116, 0x3e000000, v116
	v_mul_f32_e32 v117, 0x3e000000, v117
	v_mul_f32_e32 v118, 0x3e000000, v118
	v_mul_f32_e32 v119, 0x3e000000, v119
	v_mul_f32_e32 v120, 0x3e000000, v120
	v_mul_f32_e32 v121, 0x3e000000, v121
	v_mul_f32_e32 v122, 0x3e000000, v122
	v_mul_f32_e32 v123, 0x3e000000, v123
	v_mul_f32_e32 v124, 0x3e000000, v124
	v_mul_f32_e32 v125, 0x3e000000, v125
	v_mul_f32_e32 v126, 0x3e000000, v126
	v_mul_f32_e32 v127, 0x3e000000, v127
	v_mul_f32_e32 v128, 0x3e000000, v128
	v_mul_f32_e32 v129, 0x3e000000, v129
	v_mov_b32_e32 v200, 0xf149f2ca
	v_cmp_ge_i32_e32 vcc, 0, v160
	v_cndmask_b32_e32 v114, v200, v114, vcc
	v_cmp_ge_i32_e32 vcc, -1, v160
	v_cndmask_b32_e32 v115, v200, v115, vcc
	v_cmp_ge_i32_e32 vcc, -2, v160
	v_cndmask_b32_e32 v116, v200, v116, vcc
	v_cmp_ge_i32_e32 vcc, -3, v160
	v_cndmask_b32_e32 v117, v200, v117, vcc
	v_cmp_ge_i32_e32 vcc, -16, v160
	v_cndmask_b32_e32 v118, v200, v118, vcc
	v_cmp_ge_i32_e32 vcc, -17, v160
	v_cndmask_b32_e32 v119, v200, v119, vcc
	v_cmp_ge_i32_e32 vcc, -18, v160
	v_cndmask_b32_e32 v120, v200, v120, vcc
	v_cmp_ge_i32_e32 vcc, -19, v160
	v_cndmask_b32_e32 v121, v200, v121, vcc
	v_cmp_ge_i32_e32 vcc, -32, v160
	v_cndmask_b32_e32 v122, v200, v122, vcc
	v_cmp_ge_i32_e32 vcc, -33, v160
	v_cndmask_b32_e32 v123, v200, v123, vcc
	v_cmp_ge_i32_e32 vcc, -34, v160
	v_cndmask_b32_e32 v124, v200, v124, vcc
	v_cmp_ge_i32_e32 vcc, -35, v160
	v_cndmask_b32_e32 v125, v200, v125, vcc
	v_cmp_ge_i32_e32 vcc, -48, v160
	v_cndmask_b32_e32 v126, v200, v126, vcc
	v_cmp_ge_i32_e32 vcc, -49, v160
	v_cndmask_b32_e32 v127, v200, v127, vcc
	v_cmp_ge_i32_e32 vcc, -50, v160
	v_cndmask_b32_e32 v128, v200, v128, vcc
	v_cmp_ge_i32_e32 vcc, -51, v160
	v_cndmask_b32_e32 v129, v200, v129, vcc
	v_max3_f32 v179, v114, v115, v116
	v_max3_f32 v179, v179, v117, v118
	v_max3_f32 v179, v179, v119, v120
	v_max3_f32 v179, v179, v121, v122
	v_max3_f32 v179, v179, v123, v124
	v_max3_f32 v179, v179, v125, v126
	v_max3_f32 v179, v179, v127, v128
	v_max_f32_e32 v179, v179, v129
	ds_bpermute_b32 v201, v174, v179
	s_waitcnt lgkmcnt(0)
	v_max_f32_e32 v179, v179, v201
	ds_bpermute_b32 v201, v175, v179
	s_waitcnt lgkmcnt(0)
; DI float grp16_sum(float v) { v += __shfl_xor(v, 1); v += __shfl_xor(v, 2); v += __shfl_xor(v, 4); v += __shfl_xor(v, 8); return v; }
; template <int NKB>
; DI void attn_unit(const Params& p, int l, int mode, int grp, int head, int r0, int dil, int i0, int sub_len, int W, h16* lds) {
;     ...
; #pragma unroll
;     for (int rg = 0; rg < 4; ++rg) {
;       const float mn = fmaxf(mrow[rg], mx[rg]);
;       al[rg] = __expf(mrow[rg] - mn);
;       mrow[rg] = mn;
;       float rs_ = 0.f;
; #pragma unroll
;       for (int nt = 0; nt < 4; ++nt) {
;         float pv = vm[nt][rg] ? __expf(S[nt][rg] - mn) : 0.f;
;         rs_ += pv;
;         Pi[(16 * w + 4 * q + rg) * LDH + 16 * nt + r] = (h16)pv;
;       }
;       rsum[rg] = grp16_sum(rs_);
;       lsum[rg] = lsum[rg] * al[rg] + rsum[rg];
;     }
; #pragma unroll
;     for (int et = 0; et < 4; ++et)
; #pragma unroll
;       for (int rg = 0; rg < 4; ++rg) O[et][rg] *= al[rg];
;     __syncthreads();
;     mm64(Pi, Vt, O, w, lane);
;   }
; #pragma unroll
;   for (int rg = 0; rg < 4; ++rg) {
;     const int row = 16 * w + 4 * q + rg;
;     const size_t pos = (size_t)r0 + (size_t)dil * (i0 + row);
;     const float inv = 1.f / lsum[rg];
;     if (mode == 0) {
;       h16* ob = (h16*)(ws + OFF_OB) + ((size_t)grp * SEQ + pos) * 256 + head * 64;
; #pragma unroll
;       for (int et = 0; et < 4; ++et) ob[16 * et + r] = (h16)(O[et][rg] * inv);
;       if (r == 0) {
;         float* ml = (float*)(ws + OFF_MLB) + (((size_t)grp * SEQ + pos) * 4 + head) * 2;
;         ml[0] = mrow[rg]; ml[1] = lsum[rg];
;       }
;     } else {
;       h16* y = (h16*)(ws + OFF_Y) + pos * 1280 + 768 + head * 64;
; #pragma unroll
;       for (int et = 0; et < 4; ++et) y[16 * et + r] = (h16)(O[et][rg] * inv);
	v_max3_f32 v179, v179, v201, v176
	v_sub_f32_e32 v178, v176, v179
	v_mul_f32_e32 v178, 0x3fb8aa3b, v178
	v_exp_f32_e32 v178, v178
	v_mov_b32_e32 v176, v179
	v_mul_f32_e32 v202, 0xbfb8aa3b, v179
	v_mov_b32_e32 v203, 0x3fb8aa3b
	v_fma_f32 v114, v114, v203, v202
	v_fma_f32 v115, v115, v203, v202
	v_fma_f32 v116, v116, v203, v202
	v_fma_f32 v117, v117, v203, v202
	v_fma_f32 v118, v118, v203, v202
	v_fma_f32 v119, v119, v203, v202
	v_fma_f32 v120, v120, v203, v202
	v_fma_f32 v121, v121, v203, v202
	v_fma_f32 v122, v122, v203, v202
	v_fma_f32 v123, v123, v203, v202
	v_fma_f32 v124, v124, v203, v202
	v_fma_f32 v125, v125, v203, v202
	v_fma_f32 v126, v126, v203, v202
	v_fma_f32 v127, v127, v203, v202
	v_fma_f32 v128, v128, v203, v202
	v_fma_f32 v129, v129, v203, v202
	v_exp_f32_e32 v114, v114
	v_exp_f32_e32 v115, v115
	v_exp_f32_e32 v116, v116
	v_exp_f32_e32 v117, v117
	v_exp_f32_e32 v118, v118
	v_exp_f32_e32 v119, v119
	v_exp_f32_e32 v120, v120
	v_exp_f32_e32 v121, v121
	v_exp_f32_e32 v122, v122
	v_exp_f32_e32 v123, v123
	v_exp_f32_e32 v124, v124
	v_exp_f32_e32 v125, v125
	v_exp_f32_e32 v126, v126
	v_exp_f32_e32 v127, v127
	v_exp_f32_e32 v128, v128
	v_exp_f32_e32 v129, v129
	s_nop 0
	v_fma_f32 v177, v177, v178, v114
	v_add_f32_e32 v177, v177, v115
	v_add_f32_e32 v177, v177, v116
	v_add_f32_e32 v177, v177, v117
	v_add_f32_e32 v177, v177, v118
	v_add_f32_e32 v177, v177, v119
	v_add_f32_e32 v177, v177, v120
	v_add_f32_e32 v177, v177, v121
	v_add_f32_e32 v177, v177, v122
	v_add_f32_e32 v177, v177, v123
	v_add_f32_e32 v177, v177, v124
	v_add_f32_e32 v177, v177, v125
	v_add_f32_e32 v177, v177, v126
	v_add_f32_e32 v177, v177, v127
	v_add_f32_e32 v177, v177, v128
	v_add_f32_e32 v177, v177, v129
	v_cvt_pk_f16_f32 v130, v114, v115
	v_cvt_pk_f16_f32 v131, v116, v117
	v_cvt_pk_f16_f32 v132, v118, v119
	v_cvt_pk_f16_f32 v133, v120, v121
	v_cvt_pk_f16_f32 v134, v122, v123
	v_cvt_pk_f16_f32 v135, v124, v125
	v_cvt_pk_f16_f32 v136, v126, v127
	v_cvt_pk_f16_f32 v137, v128, v129
	v_pk_mul_f32 v[138:139], v[138:139], v[178:179] op_sel_hi:[1,0]
	v_pk_mul_f32 v[140:141], v[140:141], v[178:179] op_sel_hi:[1,0]
	v_pk_mul_f32 v[142:143], v[142:143], v[178:179] op_sel_hi:[1,0]
	v_pk_mul_f32 v[144:145], v[144:145], v[178:179] op_sel_hi:[1,0]
	v_pk_mul_f32 v[146:147], v[146:147], v[178:179] op_sel_hi:[1,0]
	v_pk_mul_f32 v[148:149], v[148:149], v[178:179] op_sel_hi:[1,0]
	v_pk_mul_f32 v[150:151], v[150:151], v[178:179] op_sel_hi:[1,0]
	v_pk_mul_f32 v[152:153], v[152:153], v[178:179] op_sel_hi:[1,0]
	s_nop 1
	v_mfma_f32_16x16x32_f16 v[138:141], v[216:219], v[130:133], v[138:141]
	v_mfma_f32_16x16x32_f16 v[142:145], v[224:227], v[130:133], v[142:145]
	v_mfma_f32_16x16x32_f16 v[146:149], v[232:235], v[130:133], v[146:149]
	v_mfma_f32_16x16x32_f16 v[150:153], v[240:243], v[130:133], v[150:153]
	v_mfma_f32_16x16x32_f16 v[138:141], v[220:223], v[134:137], v[138:141]
	v_mfma_f32_16x16x32_f16 v[142:145], v[228:231], v[134:137], v[142:145]
	v_mfma_f32_16x16x32_f16 v[146:149], v[236:239], v[134:137], v[146:149]
	v_mfma_f32_16x16x32_f16 v[150:153], v[244:247], v[134:137], v[150:153]
.Lat1_kb4_end:
	s_nop 7
	s_nop 1
	ds_bpermute_b32 v201, v174, v177
	s_waitcnt lgkmcnt(0)
	v_add_f32_e32 v177, v177, v201
	ds_bpermute_b32 v201, v175, v177
	s_waitcnt lgkmcnt(0)
	v_add_f32_e32 v177, v177, v201
	v_rcp_f32_e32 v178, v177
	s_nop 0
	v_pk_mul_f32 v[138:139], v[138:139], v[178:179] op_sel_hi:[1,0]
	v_pk_mul_f32 v[140:141], v[140:141], v[178:179] op_sel_hi:[1,0]
	v_pk_mul_f32 v[142:143], v[142:143], v[178:179] op_sel_hi:[1,0]
	v_pk_mul_f32 v[144:145], v[144:145], v[178:179] op_sel_hi:[1,0]
	v_pk_mul_f32 v[146:147], v[146:147], v[178:179] op_sel_hi:[1,0]
	v_pk_mul_f32 v[148:149], v[148:149], v[178:179] op_sel_hi:[1,0]
	v_pk_mul_f32 v[150:151], v[150:151], v[178:179] op_sel_hi:[1,0]
	v_pk_mul_f32 v[152:153], v[152:153], v[178:179] op_sel_hi:[1,0]
	v_cvt_pk_f16_f32 v130, v138, v139
	v_cvt_pk_f16_f32 v131, v140, v141
	v_cvt_pk_f16_f32 v132, v142, v143
	v_cvt_pk_f16_f32 v133, v144, v145
	v_cvt_pk_f16_f32 v134, v146, v147
	v_cvt_pk_f16_f32 v135, v148, v149
	v_cvt_pk_f16_f32 v136, v150, v151
	v_cvt_pk_f16_f32 v137, v152, v153
	global_store_dwordx2 v249, v[130:131], s[48:49]
	global_store_dwordx2 v249, v[132:133], s[48:49] offset:32
	global_store_dwordx2 v249, v[134:135], s[48:49] offset:64
	global_store_dwordx2 v249, v[136:137], s[48:49] offset:96

; DI int otid() { int t = threadIdx.x & 255; asm volatile("" : "+v"(t)); return t; }
; DI void dn_c2_unit(const Params& p, int dh, int w) {
;   unsigned char* ws = p.ws;
;   const int tid = otid(), lane = tid & 63;
;   if (tid >= 64) return;
;   const h16* cw = (const h16*)(ws + OFF_CW) + (size_t)dh * 256 * 4096;
;   const h16* ckd = (const h16*)(ws + OFF_CKD) + (size_t)dh * 256 * 4096;
;   const float* cu = (const float*)(ws + OFF_CU) + (size_t)dh * 256 * 4096;
;   const float* cdl = (const float*)(ws + OFF_CDL) + (size_t)dh * 256;
;   h16* cs = (h16*)(ws + OFF_CS) + (size_t)dh * 256 * 4096;
;   h16* cvn = (h16*)(ws + OFF_CVN) + (size_t)dh * 256 * 4096;
;   f4v S[4];
; #pragma unroll
;   for (int i = 0; i < 4; ++i) S[i] = (f4v){0.f, 0.f, 0.f, 0.f};
;   h8v wA[4][2], kA[4][2]; f4v uu[4]; float dl;
; #pragma unroll
;   for (int t = 0; t < 4; ++t) {
; #pragma unroll
;     for (int s = 0; s < 2; ++s) {
;       wA[t][s] = *(const h8v*)&cw[((t * 2 + s) * 64 + lane) * 8];
;       kA[t][s] = *(const h8v*)&ckd[((t * 2 + s) * 64 + lane) * 8];
;     }
;     uu[t] = *(const f4v*)&cu[((w * 4 + t) * 64 + lane) * 4];
;   }
;   dl = cdl[0];
;   for (int n = 0; n < 256; ++n) {
;     h8v wN[4][2], kN[4][2]; f4v uN[4]; float dlN = 0.f;
;     const int nn = (n + 1 < 256) ? n + 1 : n;
.LBB0_953:
	s_andn2_saveexec_b64 s[2:3], s[86:87]
	s_cbranch_execz .LBB0_959
	v_mov_b32_e32 v2, v182
	s_nop 0
	v_cmp_gt_i32_e32 vcc, 64, v2
	s_and_saveexec_b64 s[4:5], vcc
	s_cbranch_execz .LBB0_958
	v_ashrrev_i32_e32 v78, 2, v1
	v_ashrrev_i32_e32 v79, 31, v78
	v_readlane_b32 s6, v254, 23
	v_lshlrev_b64 v[150:151], 22, v[78:79]
	v_readlane_b32 s7, v254, 24
	v_and_b32_e32 v86, 63, v2
	v_lshlrev_b64 v[152:153], 21, v[78:79]
	v_lshl_add_u64 v[2:3], s[6:7], 0, v[150:151]
	v_readlane_b32 s6, v254, 21
	v_readlane_b32 s7, v254, 22
	v_lshlrev_b32_e32 v82, 4, v86
	v_mov_b32_e32 v83, v0
	v_lshl_add_u64 v[10:11], s[6:7], 0, v[152:153]
	v_readlane_b32 s6, v254, 25
	v_readlane_b32 s7, v254, 26
	v_lshlrev_b32_e32 v8, 10, v1
	v_lshl_add_u64 v[4:5], v[10:11], 0, v[82:83]
	v_lshl_add_u64 v[12:13], s[6:7], 0, v[152:153]
	v_lshl_add_u64 v[6:7], v[12:13], 0, v[82:83]
	v_and_b32_e32 v171, 0xc00, v8
	v_lshlrev_b32_e32 v83, 2, v86
	v_or_b32_e32 v8, v83, v171
	v_lshlrev_b32_e32 v8, 2, v8
	v_mov_b32_e32 v9, v0
	global_load_dwordx4 v[50:53], v[4:5], off
	global_load_dwordx4 v[18:21], v[4:5], off offset:1024
	global_load_dwordx4 v[70:73], v[6:7], off
	global_load_dwordx4 v[14:17], v[6:7], off offset:1024
	v_lshl_add_u64 v[84:85], v[2:3], 0, v[8:9]
	s_mov_b64 s[38:39], 0x2000
	v_lshl_add_u64 v[234:235], v[4:5], 0, s[38:39]
	v_lshl_add_u64 v[238:239], v[6:7], 0, s[38:39]
	s_mov_b64 s[40:41], 0x3000
	v_lshl_add_u64 v[236:237], v[4:5], 0, s[40:41]
	v_lshl_add_u64 v[240:241], v[6:7], 0, s[40:41]
	s_mov_b64 s[40:41], 0x4000
	v_lshl_add_u64 v[242:243], v[84:85], 0, s[40:41]
	global_load_dwordx4 v[26:29], v[4:5], off offset:2048
	global_load_dwordx4 v[22:25], v[4:5], off offset:3072
	global_load_dwordx4 v[38:41], v[6:7], off offset:2048
	s_nop 0
	global_load_dwordx4 v[2:5], v[6:7], off offset:3072
	global_load_dwordx4 v[58:61], v[84:85], off
	global_load_dwordx4 v[54:57], v[84:85], off offset:1024
	v_or_b32_e32 v6, 0x1000, v82
	v_mov_b32_e32 v7, v0
	v_lshl_add_u64 v[8:9], v[10:11], 0, v[6:7]
	v_lshl_add_u64 v[6:7], v[12:13], 0, v[6:7]
	global_load_dwordx4 v[34:37], v[8:9], off
	global_load_dwordx4 v[30:33], v[6:7], off
	v_or_b32_e32 v6, 0x1400, v82
	v_mov_b32_e32 v7, v0
	v_or_b32_e32 v42, 0x1800, v82
	v_mov_b32_e32 v43, v0
	v_or_b32_e32 v66, 0x1c00, v82
	v_mov_b32_e32 v67, v0
	v_lshl_add_u64 v[8:9], v[10:11], 0, v[6:7]
	v_lshl_add_u64 v[6:7], v[12:13], 0, v[6:7]
	v_lshl_add_u64 v[44:45], v[10:11], 0, v[42:43]
	v_lshl_add_u64 v[42:43], v[12:13], 0, v[42:43]
	v_lshl_add_u64 v[10:11], v[10:11], 0, v[66:67]
	v_lshl_add_u64 v[12:13], v[12:13], 0, v[66:67]
	v_readlane_b32 s6, v254, 19
	v_lshlrev_b64 v[80:81], 10, v[78:79]
	global_load_dwordx4 v[46:49], v[8:9], off
	s_nop 0
	global_load_dwordx4 v[6:9], v[6:7], off
	s_nop 0
	global_load_dwordx4 v[62:65], v[44:45], off
	s_nop 0
	global_load_dwordx4 v[42:45], v[42:43], off
	s_nop 0
	global_load_dwordx4 v[66:69], v[10:11], off
	s_nop 0
	global_load_dwordx4 v[10:13], v[12:13], off
	s_nop 0
	global_load_dwordx4 v[74:77], v[84:85], off offset:2048
	global_load_dwordx4 v[90:93], v[84:85], off offset:3072
	v_readlane_b32 s7, v254, 20
	v_lshlrev_b32_e32 v174, 3, v86
	v_lshlrev_b64 v[154:155], 20, v[78:79]
	v_lshl_add_u64 v[84:85], s[6:7], 0, v[80:81]
	v_lshl_add_u64 v[244:245], v[84:85], 0, 4
	global_load_dword v160, v[84:85], off
	v_and_b32_e32 v84, 0xc00, v164
	v_or_b32_e32 v78, v84, v174
	v_lshl_or_b32 v158, v78, 1, v152
	v_or_b32_e32 v78, v84, v83
	v_readlane_b32 s16, v252, 3
	s_mov_b64 s[6:7], 0x1df08004
	v_lshl_or_b32 v150, v78, 2, v150
	v_mov_b32_e32 v78, 0
	v_readlane_b32 s17, v252, 4
	v_lshl_add_u64 v[156:157], v[80:81], 0, s[6:7]
	v_mov_b32_e32 v159, v153
	v_or_b32_e32 v152, v152, v82
	s_movk_i32 s6, 0xff
	v_mov_b32_e32 v79, v78
	v_mov_b32_e32 v80, v78
	v_mov_b32_e32 v81, v78
	v_mov_b32_e32 v94, v78
	v_mov_b32_e32 v95, v78
	v_mov_b32_e32 v96, v78
	v_mov_b32_e32 v97, v78
	v_mov_b32_e32 v86, v78
	v_mov_b32_e32 v87, v78
	v_mov_b32_e32 v88, v78
	v_mov_b32_e32 v89, v78
	v_mov_b32_e32 v82, v78
	v_mov_b32_e32 v83, v78
	v_mov_b32_e32 v84, v78
	v_mov_b32_e32 v85, v78
	v_readlane_b32 s20, v252, 7
	v_readlane_b32 s21, v252, 8
	s_mov_b64 s[16:17], 0x2000
	v_readlane_b32 s18, v252, 5
	v_readlane_b32 s19, v252, 6
	v_readlane_b32 s22, v252, 9
	v_readlane_b32 s23, v252, 10
	v_readfirstlane_b32 s37, v183
	v_and_b32_e32 v247, 63, v182
	v_lshlrev_b32_e32 v247, 4, v247
	s_cmp_eq_u32 s37, 16
	s_cselect_b32 s37, 16, 0xfc10
	s_add_u32 s36, s37, 0xfc00
	s_add_u32 s34, s37, 0x5400
	s_waitcnt vmcnt(21)
; DI void dn_c2_unit(const Params& p, int dh, int w) {
;     ...
;   for (int n = 0; n < 256; ++n) {
;     h8v wN[4][2], kN[4][2]; f4v uN[4]; float dlN = 0.f;
;     const int nn = (n + 1 < 256) ? n + 1 : n;
;     {
;       const h16* cw1 = cw + (size_t)nn * 4096; const h16* ck1 = ckd + (size_t)nn * 4096; const float* cu1 = cu + (size_t)nn * 4096;
; #pragma unroll
;       for (int t = 0; t < 4; ++t) {
; #pragma unroll
;         for (int s = 0; s < 2; ++s) {
;           wN[t][s] = *(const h8v*)&cw1[((t * 2 + s) * 64 + lane) * 8];
;           kN[t][s] = *(const h8v*)&ck1[((t * 2 + s) * 64 + lane) * 8];
;         }
;         uN[t] = *(const f4v*)&cu1[((w * 4 + t) * 64 + lane) * 4];
;       }
;       dlN = cdl[nn];
;     }
	s_mov_b32 m0, s34
	s_nop 0
	global_load_lds_dwordx4 v[234:235], off
	global_load_lds_dwordx4 v[234:235], off offset:1024
	global_load_lds_dwordx4 v[234:235], off offset:2048
	global_load_lds_dwordx4 v[234:235], off offset:3072
	s_add_u32 m0, s34, 0x1000
	s_nop 0
	global_load_lds_dwordx4 v[236:237], off
	global_load_lds_dwordx4 v[236:237], off offset:1024
	global_load_lds_dwordx4 v[236:237], off offset:2048
	global_load_lds_dwordx4 v[236:237], off offset:3072
	s_add_u32 m0, s34, 0x2000
	s_nop 0
	global_load_lds_dwordx4 v[238:239], off
	global_load_lds_dwordx4 v[238:239], off offset:1024
	global_load_lds_dwordx4 v[238:239], off offset:2048
	global_load_lds_dwordx4 v[238:239], off offset:3072
	s_add_u32 m0, s34, 0x3000
	s_nop 0
	global_load_lds_dwordx4 v[240:241], off
	global_load_lds_dwordx4 v[240:241], off offset:1024
	global_load_lds_dwordx4 v[240:241], off offset:2048
	global_load_lds_dwordx4 v[240:241], off offset:3072
	s_add_u32 m0, s34, 0x4000
	s_nop 0
	global_load_lds_dwordx4 v[242:243], off
	global_load_lds_dwordx4 v[242:243], off offset:1024
	global_load_lds_dwordx4 v[242:243], off offset:2048
	global_load_lds_dwordx4 v[242:243], off offset:3072
	s_add_u32 m0, s34, 0x5000
	s_nop 0
	global_load_lds_dword v[244:245], off
	v_lshl_add_u64 v[234:235], v[234:235], 0, s[38:39]
	v_lshl_add_u64 v[236:237], v[236:237], 0, s[38:39]
	v_lshl_add_u64 v[238:239], v[238:239], 0, s[38:39]
	v_lshl_add_u64 v[240:241], v[240:241], 0, s[38:39]
	v_lshl_add_u64 v[242:243], v[242:243], 0, s[40:41]
	v_lshl_add_u64 v[244:245], v[244:245], 0, 4
	s_add_u32 s34, s34, 0x5400
	s_mov_b32 m0, s34
	s_nop 0
	global_load_lds_dwordx4 v[234:235], off
	global_load_lds_dwordx4 v[234:235], off offset:1024
	global_load_lds_dwordx4 v[234:235], off offset:2048
	global_load_lds_dwordx4 v[234:235], off offset:3072
	s_add_u32 m0, s34, 0x1000
	s_nop 0
	global_load_lds_dwordx4 v[236:237], off
	global_load_lds_dwordx4 v[236:237], off offset:1024
	global_load_lds_dwordx4 v[236:237], off offset:2048
	global_load_lds_dwordx4 v[236:237], off offset:3072
	s_add_u32 m0, s34, 0x2000
	s_nop 0
	global_load_lds_dwordx4 v[238:239], off
	global_load_lds_dwordx4 v[238:239], off offset:1024
	global_load_lds_dwordx4 v[238:239], off offset:2048
	global_load_lds_dwordx4 v[238:239], off offset:3072
	s_add_u32 m0, s34, 0x3000
	s_nop 0
	global_load_lds_dwordx4 v[240:241], off
	global_load_lds_dwordx4 v[240:241], off offset:1024
	global_load_lds_dwordx4 v[240:241], off offset:2048
	global_load_lds_dwordx4 v[240:241], off offset:3072
	s_add_u32 m0, s34, 0x4000
	s_nop 0
	global_load_lds_dwordx4 v[242:243], off
	global_load_lds_dwordx4 v[242:243], off offset:1024
	global_load_lds_dwordx4 v[242:243], off offset:2048
	global_load_lds_dwordx4 v[242:243], off offset:3072
	s_add_u32 m0, s34, 0x5000
	s_nop 0
	global_load_lds_dword v[244:245], off
	v_lshl_add_u64 v[234:235], v[234:235], 0, s[38:39]
	v_lshl_add_u64 v[236:237], v[236:237], 0, s[38:39]
	v_lshl_add_u64 v[238:239], v[238:239], 0, s[38:39]
	v_lshl_add_u64 v[240:241], v[240:241], 0, s[38:39]
	v_lshl_add_u64 v[242:243], v[242:243], 0, s[40:41]
	v_lshl_add_u64 v[244:245], v[244:245], 0, 4
	s_mov_b32 s34, s37
	s_add_u32 s35, s37, 0x5400
	s_waitcnt vmcnt(42)
.LBB0_956:
	s_mov_b32 m0, s34
	s_nop 0
	global_load_lds_dwordx4 v[234:235], off
	global_load_lds_dwordx4 v[234:235], off offset:1024
	global_load_lds_dwordx4 v[234:235], off offset:2048
	global_load_lds_dwordx4 v[234:235], off offset:3072
	s_add_u32 m0, s34, 0x1000
	s_nop 0
	global_load_lds_dwordx4 v[236:237], off
	global_load_lds_dwordx4 v[236:237], off offset:1024
	global_load_lds_dwordx4 v[236:237], off offset:2048
	global_load_lds_dwordx4 v[236:237], off offset:3072
	s_add_u32 m0, s34, 0x2000
	s_nop 0
	global_load_lds_dwordx4 v[238:239], off
	global_load_lds_dwordx4 v[238:239], off offset:1024
	global_load_lds_dwordx4 v[238:239], off offset:2048
	global_load_lds_dwordx4 v[238:239], off offset:3072
	s_add_u32 m0, s34, 0x3000
	s_nop 0
	global_load_lds_dwordx4 v[240:241], off
	s_cmp_gt_u32 s6, 253
	s_cbranch_scc1 .Lscan_early_wait
	s_waitcnt vmcnt(42)
	s_branch .Lscan_wait_done
.Lscan_early_wait:
	s_waitcnt vmcnt(34)
.Lscan_wait_done:
	global_load_lds_dwordx4 v[240:241], off offset:1024
	global_load_lds_dwordx4 v[240:241], off offset:2048
	global_load_lds_dwordx4 v[240:241], off offset:3072
	s_add_u32 m0, s34, 0x4000
	s_nop 0
	global_load_lds_dwordx4 v[242:243], off
	global_load_lds_dwordx4 v[242:243], off offset:1024
	global_load_lds_dwordx4 v[242:243], off offset:2048
	global_load_lds_dwordx4 v[242:243], off offset:3072
	s_add_u32 m0, s34, 0x5000
	s_nop 0
	global_load_lds_dword v[244:245], off
	v_lshl_add_u64 v[234:235], v[234:235], 0, s[38:39]
	v_lshl_add_u64 v[236:237], v[236:237], 0, s[38:39]
	v_lshl_add_u64 v[238:239], v[238:239], 0, s[38:39]
	v_lshl_add_u64 v[240:241], v[240:241], 0, s[38:39]
	v_lshl_add_u64 v[242:243], v[242:243], 0, s[40:41]
	v_lshl_add_u64 v[244:245], v[244:245], 0, 4
	v_add_u32_e32 v246, s35, v247
	v_mov_b32_e32 v248, s35
	s_add_u32 s34, s34, 0x5400
	s_cmp_ge_u32 s34, s36
	s_cselect_b32 s34, s37, s34
	s_add_u32 s35, s35, 0x5400
	s_cmp_ge_u32 s35, s36
	s_cselect_b32 s35, s37, s35
	v_mov_b64_e32 v[178:179], v[20:21]
	v_mov_b64_e32 v[176:177], v[18:19]
	v_mov_b64_e32 v[148:149], v[24:25]
	v_mov_b64_e32 v[146:147], v[22:23]
	s_nop 0
	v_mov_b64_e32 v[132:133], v[28:29]
	v_mov_b64_e32 v[140:141], v[36:37]
	v_mov_b64_e32 v[130:131], v[26:27]
	v_mov_b64_e32 v[138:139], v[34:35]
	v_mov_b64_e32 v[218:219], v[64:65]
	v_mov_b64_e32 v[216:217], v[62:63]
	v_mov_b64_e32 v[120:121], v[60:61]
	v_mov_b64_e32 v[128:129], v[56:57]
	v_mov_b64_e32 v[118:119], v[58:59]
	v_mov_b64_e32 v[126:127], v[54:55]
; DI f4v mfma16(h8v a, h8v b, f4v c) { return __builtin_amdgcn_mfma_f32_16x16x32_f16(a, b, c, 0, 0, 0); }
; DI void dn_c2_unit(const Params& p, int dh, int w) {
;     ...
;     h8v Sb[2];
;     Sb[0] = pack8(S[0], S[1]); Sb[1] = pack8(S[2], S[3]);
;     h16* cs1 = cs + (size_t)n * 4096; h16* cv1 = cvn + (size_t)n * 4096;
;     *(h8v*)&cs1[((w * 2 + 0) * 64 + lane) * 8] = Sb[0];
;     *(h8v*)&cs1[((w * 2 + 1) * 64 + lane) * 8] = Sb[1];
;     f4v vn[4];
; #pragma unroll
;     for (int t = 0; t < 4; ++t) { vn[t] = uu[t]; vn[t] = mfma16(wA[t][0], Sb[0], vn[t]); vn[t] = mfma16(wA[t][1], Sb[1], vn[t]); }
;     h8v Vb[2];
;     Vb[0] = pack8(vn[0], vn[1]); Vb[1] = pack8(vn[2], vn[3]);
;     *(h8v*)&cv1[((w * 2 + 0) * 64 + lane) * 8] = Vb[0];
;     *(h8v*)&cv1[((w * 2 + 1) * 64 + lane) * 8] = Vb[1];
; #pragma unroll
;     for (int t = 0; t < 4; ++t) { S[t] *= dl; S[t] = mfma16(kA[t][0], Vb[0], S[t]); S[t] = mfma16(kA[t][1], Vb[1], S[t]); }
; #pragma unroll
;     for (int t = 0; t < 4; ++t) { wA[t][0] = wN[t][0]; wA[t][1] = wN[t][1]; kA[t][0] = kN[t][0]; kA[t][1] = kN[t][1]; uu[t] = uN[t]; }
;     dl = dlN;
;   }
	v_mov_b64_e32 v[144:145], v[48:49]
	v_cvt_pk_f16_f32 v101, v96, v97
	v_cvt_pk_f16_f32 v100, v94, v95
	v_cvt_pk_f16_f32 v99, v80, v81
	v_cvt_pk_f16_f32 v98, v78, v79
	v_mov_b64_e32 v[142:143], v[46:47]
	v_mov_b64_e32 v[136:137], v[68:69]
	ds_read_b128 v[18:21], v246 offset:1024
	ds_read_b128 v[26:29], v246 offset:2048
	ds_read_b128 v[106:109], v246 offset:9216
	s_nop 0
	ds_read_b128 v[22:25], v246 offset:3072
	s_nop 0
	ds_read_b128 v[110:113], v246 offset:10240
	ds_read_b128 v[114:117], v246 offset:11264
	ds_read_b128 v[58:61], v246 offset:16384
	ds_read_b128 v[54:57], v246 offset:17408
	v_mfma_f32_16x16x32_f16 v[220:223], v[50:53], v[98:101], v[118:121]
	ds_read_b128 v[34:37], v246 offset:4096
	s_nop 1
	ds_read_b128 v[118:121], v246 offset:8192
	ds_read_b128 v[122:125], v246 offset:12288
	v_mov_b64_e32 v[134:135], v[66:67]
	v_mfma_f32_16x16x32_f16 v[224:227], v[130:133], v[98:101], v[126:129]
	ds_read_b128 v[46:49], v246 offset:5120
	s_nop 1
	ds_read_b128 v[126:129], v246 offset:13312
	ds_read_b128 v[130:133], v246 offset:15360
	v_cvt_pk_f16_f32 v105, v84, v85
	v_cvt_pk_f16_f32 v104, v82, v83
	v_mfma_f32_16x16x32_f16 v[228:231], v[138:141], v[98:101], v[74:77]
	ds_read_b128 v[138:141], v246 offset:14336
	s_nop 1
	ds_read_b128 v[74:77], v246 offset:18432
	ds_read_b128 v[62:65], v246 offset:6144
	ds_read_b128 v[66:69], v246 offset:7168
	ds_read_b128 v[50:53], v246
	ds_read_b32 v175, v248 offset:20480
	v_cvt_pk_f16_f32 v103, v88, v89
	v_mfma_f32_16x16x32_f16 v[216:219], v[216:219], v[98:101], v[90:93]
	v_cvt_pk_f16_f32 v102, v86, v87
	v_pk_mul_f32 v[80:81], v[160:161], v[80:81] op_sel_hi:[0,1]
	v_pk_mul_f32 v[78:79], v[160:161], v[78:79] op_sel_hi:[0,1]
	ds_read_b128 v[90:93], v246 offset:19456
	v_mfma_f32_16x16x32_f16 v[176:179], v[176:179], v[102:105], v[220:223]
	v_mul_f32_e64 v96, v160, v96
	v_mul_f32_e64 v97, v160, v97
	v_pk_mul_f32 v[94:95], v[160:161], v[94:95] op_sel_hi:[0,1]
	v_pk_mul_f32 v[88:89], v[160:161], v[88:89] op_sel_hi:[0,1]
	v_mfma_f32_16x16x32_f16 v[146:149], v[146:149], v[102:105], v[224:227]
	v_mul_f32_e64 v86, v160, v86
	v_mul_f32_e64 v87, v160, v87
	v_pk_mul_f32 v[84:85], v[160:161], v[84:85] op_sel_hi:[0,1]
	v_pk_mul_f32 v[82:83], v[160:161], v[82:83] op_sel_hi:[0,1]
	v_mfma_f32_16x16x32_f16 v[142:145], v[142:145], v[102:105], v[228:231]
	v_lshl_add_u64 v[200:201], s[20:21], 0, v[158:159]
	s_nop 1
	v_cvt_pk_f16_f32 v149, v148, v149
	v_cvt_pk_f16_f32 v148, v146, v147
	v_mfma_f32_16x16x32_f16 v[134:137], v[134:137], v[102:105], v[216:219]
	v_cvt_pk_f16_f32 v147, v178, v179
	v_cvt_pk_f16_f32 v146, v176, v177
	s_mov_b32 s7, 0x1df0a000
	v_add_co_u32_e32 v176, vcc, s7, v200
	v_mfma_f32_16x16x32_f16 v[70:73], v[70:73], v[146:149], v[78:81]
	s_nop 2
	v_cvt_pk_f16_f32 v137, v136, v137
	v_cvt_pk_f16_f32 v136, v134, v135
	v_cvt_pk_f16_f32 v135, v144, v145
	v_mfma_f32_16x16x32_f16 v[38:41], v[38:41], v[146:149], v[94:97]
	v_cvt_pk_f16_f32 v134, v142, v143
	v_addc_co_u32_e32 v177, vcc, 0, v201, vcc
	v_mfma_f32_16x16x32_f16 v[30:33], v[30:33], v[146:149], v[86:89]
	s_mov_b32 s7, 0x1ef0a000
	s_add_i32 s6, s6, -1
	s_mov_b64 s[8:9], 0x4000
	v_mfma_f32_16x16x32_f16 v[42:45], v[42:45], v[146:149], v[82:85]
	global_store_dwordx4 v[176:177], v[98:101], off
	v_lshl_add_u64 v[156:157], v[156:157], 0, 4
	v_lshl_add_u64 v[158:159], v[158:159], 0, s[16:17]
	v_mfma_f32_16x16x32_f16 v[78:81], v[14:17], v[134:137], v[70:73]
	v_add_co_u32_e32 v14, vcc, s7, v200
	v_lshl_add_u64 v[150:151], v[150:151], 0, s[8:9]
	v_mfma_f32_16x16x32_f16 v[94:97], v[2:5], v[134:137], v[38:41]
	v_addc_co_u32_e32 v15, vcc, 0, v201, vcc
	global_store_dwordx4 v[176:177], v[102:105], off offset:1024
	global_store_dwordx4 v[14:15], v[146:149], off
	global_store_dwordx4 v[14:15], v[134:137], off offset:1024
	v_mfma_f32_16x16x32_f16 v[86:89], v[6:9], v[134:137], v[30:33]
	v_lshl_add_u64 v[152:153], v[152:153], 0, s[16:17]
	s_cmp_eq_u32 s6, 0
	s_waitcnt lgkmcnt(0)
	v_mov_b64_e32 v[14:15], v[106:107]
	v_mfma_f32_16x16x32_f16 v[82:85], v[10:13], v[134:137], v[42:45]
	v_mov_b64_e32 v[38:39], v[110:111]
	v_mov_b64_e32 v[2:3], v[114:115]
	v_mov_b64_e32 v[4:5], v[116:117]
	v_mov_b64_e32 v[40:41], v[112:113]
	v_mov_b64_e32 v[70:71], v[118:119]
	v_mov_b64_e32 v[30:31], v[122:123]
	v_mov_b64_e32 v[32:33], v[124:125]
	v_mov_b64_e32 v[16:17], v[108:109]
	v_mov_b64_e32 v[6:7], v[126:127]
	v_mov_b64_e32 v[10:11], v[130:131]
	v_mov_b64_e32 v[12:13], v[132:133]
	v_mov_b64_e32 v[42:43], v[138:139]
	v_mov_b64_e32 v[44:45], v[140:141]
	v_mov_b64_e32 v[8:9], v[128:129]
	v_mov_b64_e32 v[72:73], v[120:121]
	v_mov_b32_e32 v160, v175
	s_cbranch_scc0 .LBB0_956
	v_cvt_pk_f16_f32 v5, v96, v97
	v_cvt_pk_f16_f32 v4, v94, v95
	v_cvt_pk_f16_f32 v3, v80, v81
	v_cvt_pk_f16_f32 v2, v78, v79
	v_cvt_pk_f16_f32 v9, v84, v85
	v_cvt_pk_f16_f32 v8, v82, v83
	v_mfma_f32_16x16x32_f16 v[10:13], v[50:53], v[2:5], v[58:61]
	v_cvt_pk_f16_f32 v7, v88, v89
	v_cvt_pk_f16_f32 v6, v86, v87
	v_readlane_b32 s6, v254, 36
	v_mfma_f32_16x16x32_f16 v[14:17], v[26:29], v[2:5], v[54:57]
	v_readlane_b32 s7, v254, 37
	v_mfma_f32_16x16x32_f16 v[10:13], v[18:21], v[6:9], v[10:13]
	v_lshlrev_b64 v[18:19], 1, v[154:155]
	v_lshl_add_u64 v[20:21], s[6:7], 0, v[18:19]
	v_readlane_b32 s6, v254, 38
	v_readlane_b32 s7, v254, 39
	v_mfma_f32_16x16x32_f16 v[14:17], v[22:25], v[6:9], v[14:17]
	v_mov_b32_e32 v23, v0
	v_lshl_add_u64 v[26:27], s[6:7], 0, v[18:19]
	v_or_b32_e32 v18, v174, v171
	s_mov_b64 s[6:7], 0x1fe000
	v_lshlrev_b32_e32 v22, 1, v18
	v_lshl_add_u64 v[24:25], v[20:21], 0, s[6:7]
	v_lshl_add_u64 v[28:29], v[24:25], 0, v[22:23]
	v_mfma_f32_16x16x32_f16 v[18:21], v[34:37], v[2:5], v[74:77]
	global_store_dwordx4 v[28:29], v[2:5], off
	v_or_b32_e32 v28, 0x400, v22
	v_mov_b32_e32 v29, v0
	s_waitcnt vmcnt(5)
	v_mfma_f32_16x16x32_f16 v[2:5], v[62:65], v[2:5], v[90:93]
	v_lshl_add_u64 v[24:25], v[24:25], 0, v[28:29]
	global_store_dwordx4 v[24:25], v[6:9], off
	v_lshl_add_u64 v[24:25], v[26:27], 0, s[6:7]
	v_mfma_f32_16x16x32_f16 v[18:21], v[46:49], v[6:9], v[18:21]
	v_cvt_pk_f16_f32 v17, v16, v17
	v_cvt_pk_f16_f32 v16, v14, v15
	v_cvt_pk_f16_f32 v15, v12, v13
	v_mfma_f32_16x16x32_f16 v[2:5], v[66:69], v[6:9], v[2:5]
	v_cvt_pk_f16_f32 v14, v10, v11
	v_lshl_add_u64 v[6:7], v[24:25], 0, v[22:23]
	global_store_dwordx4 v[6:7], v[14:17], off
	v_lshl_add_u64 v[6:7], v[24:25], 0, v[28:29]
	s_nop 3
	v_cvt_pk_f16_f32 v5, v4, v5
	v_cvt_pk_f16_f32 v4, v2, v3
	v_cvt_pk_f16_f32 v3, v20, v21
	v_cvt_pk_f16_f32 v2, v18, v19
	global_store_dwordx4 v[6:7], v[2:5], off
	s_waitcnt vmcnt(0)
